# GEMM K-loops: per-segment s_setprio toggling removed (s_nop 0 placeholders)
# speedup vs baseline: 1.0038x; 1.0038x over previous
; #define PG8_STAGE(bufoff, gbase, voff) do { _Pragma("unroll") for (int _i = 0; _i < 2; ++_i) \
;         __builtin_amdgcn_global_load_lds((const unsigned*)((const char*)(gbase) + (voff)[_i]), (PG8_LAS unsigned*)(lds + (bufoff) + ldsw + _i * 8192), 16, 0, 0); } while (0)
; #define PG8_LDA(dst, b, h) do { _Pragma("unroll") for (int m = 0; m < 4; ++m) _Pragma("unroll") for (int k = 0; k < 2; ++k) dst[m][k] = *(const PG8_LAS bf16x8*)(lds + PG8_SA(b, h) + aoff + m * 2048 + k * 1024); } while (0)
; #define PG8_LDB(dst, b, h) do { _Pragma("unroll") for (int n = 0; n < 2; ++n) _Pragma("unroll") for (int k = 0; k < 2; ++k) dst[n][k] = *(const PG8_LAS bf16x8*)(lds + PG8_SB(b, h) + boff + n * 2048 + k * 1024); } while (0)
; #define PG8_MMA(ai, bj, At, Bt) do { __builtin_amdgcn_s_setprio(1); _Pragma("unroll") for (int m = 0; m < 4; ++m) _Pragma("unroll") for (int n = 0; n < 2; ++n) _Pragma("unroll") for (int k = 0; k < 2; ++k) \
;         acc[ai][bj][m][n] = __builtin_amdgcn_mfma_f32_16x16x32_bf16(Bt[n][k], At[m][k], acc[ai][bj][m][n], 0, 0, 0); __builtin_amdgcn_s_setprio(0); } while (0)
; #define PG8_WAIT_V(n) asm volatile("s_waitcnt vmcnt(" #n ")" ::: "memory")
; #define PG8_WAIT_L(n) asm volatile("s_waitcnt lgkmcnt(" #n ")" ::: "memory")
; #define PG8_BAR __builtin_amdgcn_s_barrier()
; #define PG8_SCHED __builtin_amdgcn_sched_barrier(0)
; template <class Epi, class Sched, bool ALIGN_EPI = false, bool SP2 = false>
; __device__ __forceinline__ void gemm_phase(PG8_LAS unsigned char* lds, const Gemm g, const Sched& S, const Epi& E, int wv) {
;     ...
;             const bool last = (t == nt - 2);
;             const char* a1 = cA + (size_t)(t + 1) * kstep;
;             const char* a2 = last ? nA : cA + (size_t)(t + 2) * kstep; const char* b2 = last ? nB : cB + (size_t)(t + 2) * kstep;
;             const char* a3 = a2 + kstep; const char* b3 = b2 + kstep;
;             if (last && has_next) S.a_ready(nxt);
;             if constexpr (SP2) {
;             PG8_LDB(B0, 0, 0); PG8_LDB(B1, 0, 1); PG8_SCHED; PG8_LDA(At, 0, 0); PG8_STAGE(PG8_SA(1, 1), a1 + hstepA, voffA);
;             PG8_WAIT_V(8); PG8_WAIT_L(0); PG8_BAR; PG8_MMA(0, 0, At, B0); PG8_MMA(0, 1, At, B1); PG8_BAR; PG8_SCHED;
;             PG8_LDA(At, 0, 1); PG8_STAGE(PG8_SB(0, 0), b2, voffB); PG8_STAGE(PG8_SB(0, 1), b2 + hstepB, voffB); PG8_STAGE(PG8_SA(0, 0), a2, voffA);
.LBB0_663:
	s_add_u32 s2, s34, 0xfffc0080
	s_addc_u32 s3, s35, -1
	s_add_i32 s22, 0, 0x10000
	s_cmp_eq_u32 vcc_lo, 12
	s_cselect_b32 s51, s15, s3
	s_cselect_b32 s50, s19, s2
	s_cselect_b32 s3, s43, s97
	s_cselect_b32 s2, s45, s96
	s_add_i32 s60, 0, 0x14000
	v_add_u32_e32 v156, s22, v146
	v_add_u32_e32 v172, s60, v146
	ds_read_b128 v[140:143], v156
	ds_read_b128 v[148:151], v156 offset:1024
	ds_read_b128 v[152:155], v156 offset:2048
	ds_read_b128 v[156:159], v156 offset:3072
	ds_read_b128 v[160:163], v172
	ds_read_b128 v[164:167], v172 offset:1024
	ds_read_b128 v[168:171], v172 offset:2048
	ds_read_b128 v[172:175], v172 offset:3072
	v_lshl_add_u64 v[196:197], s[34:35], 0, v[136:137]
	s_add_i32 m0, s21, 0xc000
	ds_read_b128 v[176:179], v147
	ds_read_b128 v[180:183], v147 offset:1024
	ds_read_b128 v[184:187], v147 offset:2048
	ds_read_b128 v[242:245], v147 offset:3072
	ds_read_b128 v[246:249], v147 offset:4096
	ds_read_b128 v[250:253], v147 offset:5120
	ds_read_b128 v[220:223], v147 offset:6144
	ds_read_b128 v[224:227], v147 offset:7168
	global_load_lds_dwordx4 v[196:197], off
	v_lshl_add_u64 v[196:197], s[34:35], 0, v[138:139]
	s_add_i32 m0, s21, 0xe000
	s_nop 0
	global_load_lds_dwordx4 v[196:197], off
	s_waitcnt vmcnt(8)
	s_waitcnt lgkmcnt(0)
	s_barrier
	s_nop 0
	s_waitcnt lgkmcnt(0)
	v_mfma_f32_16x16x32_bf16 v[126:129], v[140:143], v[176:179], v[126:129]
	v_mfma_f32_16x16x32_bf16 v[122:125], v[152:155], v[176:179], v[122:125]
	v_mfma_f32_16x16x32_bf16 v[110:113], v[140:143], v[184:187], v[110:113]
	v_mfma_f32_16x16x32_bf16 v[106:109], v[152:155], v[184:187], v[106:109]
	v_mfma_f32_16x16x32_bf16 v[94:97], v[140:143], v[246:249], v[94:97]
	v_mfma_f32_16x16x32_bf16 v[90:93], v[152:155], v[246:249], v[90:93]
	v_mfma_f32_16x16x32_bf16 v[78:81], v[140:143], v[220:223], v[78:81]
	v_mfma_f32_16x16x32_bf16 v[74:77], v[152:155], v[220:223], v[74:77]
	v_mfma_f32_16x16x32_bf16 v[126:129], v[148:151], v[180:183], v[126:129]
	v_mfma_f32_16x16x32_bf16 v[122:125], v[156:159], v[180:183], v[122:125]
	v_mfma_f32_16x16x32_bf16 v[110:113], v[148:151], v[242:245], v[110:113]
	v_mfma_f32_16x16x32_bf16 v[106:109], v[156:159], v[242:245], v[106:109]
	v_mfma_f32_16x16x32_bf16 v[94:97], v[148:151], v[250:253], v[94:97]
	v_mfma_f32_16x16x32_bf16 v[90:93], v[156:159], v[250:253], v[90:93]
	v_mfma_f32_16x16x32_bf16 v[78:81], v[148:151], v[224:227], v[78:81]
	v_mfma_f32_16x16x32_bf16 v[74:77], v[156:159], v[224:227], v[74:77]
	s_nop 0
	s_nop 0
	v_mfma_f32_16x16x32_bf16 v[118:121], v[160:163], v[176:179], v[118:121]
	v_mfma_f32_16x16x32_bf16 v[114:117], v[168:171], v[176:179], v[114:117]
	v_mfma_f32_16x16x32_bf16 v[102:105], v[160:163], v[184:187], v[102:105]
	v_mfma_f32_16x16x32_bf16 v[98:101], v[168:171], v[184:187], v[98:101]
	v_mfma_f32_16x16x32_bf16 v[86:89], v[160:163], v[246:249], v[86:89]
	v_mfma_f32_16x16x32_bf16 v[82:85], v[168:171], v[246:249], v[82:85]
	v_mfma_f32_16x16x32_bf16 v[70:73], v[160:163], v[220:223], v[70:73]
	v_mfma_f32_16x16x32_bf16 v[66:69], v[168:171], v[220:223], v[66:69]
	v_mfma_f32_16x16x32_bf16 v[118:121], v[164:167], v[180:183], v[118:121]
	v_mfma_f32_16x16x32_bf16 v[114:117], v[172:175], v[180:183], v[114:117]
	v_mfma_f32_16x16x32_bf16 v[102:105], v[164:167], v[242:245], v[102:105]
	v_mfma_f32_16x16x32_bf16 v[98:101], v[172:175], v[242:245], v[98:101]
	v_mfma_f32_16x16x32_bf16 v[86:89], v[164:167], v[250:253], v[86:89]
	v_mfma_f32_16x16x32_bf16 v[82:85], v[172:175], v[250:253], v[82:85]
	v_mfma_f32_16x16x32_bf16 v[70:73], v[164:167], v[224:227], v[70:73]
	v_mfma_f32_16x16x32_bf16 v[66:69], v[172:175], v[224:227], v[66:69]
	s_nop 0
	s_barrier
	s_add_i32 s22, s22, s55
	v_lshl_add_u64 v[196:197], s[2:3], 0, v[0:1]
	s_mov_b32 m0, s22
	ds_read_b128 v[176:179], v147 offset:16384
	ds_read_b128 v[180:183], v147 offset:17408
	ds_read_b128 v[184:187], v147 offset:18432
	ds_read_b128 v[220:223], v147 offset:19456
	ds_read_b128 v[224:227], v147 offset:20480
	ds_read_b128 v[242:245], v147 offset:21504
	ds_read_b128 v[246:249], v147 offset:22528
	ds_read_b128 v[250:253], v147 offset:23552
	global_load_lds_dwordx4 v[196:197], off
	s_add_i32 m0, s22, 0x2000
	s_add_u32 s22, s2, 0x40000
	v_lshl_add_u64 v[228:229], s[2:3], 0, v[134:135]
	s_addc_u32 s23, s3, 0
	s_add_i32 s60, s60, s55
	global_load_lds_dwordx4 v[228:229], off
	v_lshl_add_u64 v[230:231], s[22:23], 0, v[0:1]
	s_mov_b32 m0, s60
	v_lshl_add_u64 v[232:233], s[50:51], 0, v[132:133]
	global_load_lds_dwordx4 v[230:231], off
	v_lshl_add_u64 v[230:231], s[22:23], 0, v[134:135]
	s_add_i32 m0, s60, 0x2000
	s_nop 0
	global_load_lds_dwordx4 v[230:231], off
	v_lshl_add_u64 v[230:231], s[50:51], 0, v[130:131]
	s_mov_b32 m0, s21
	s_nop 0
	global_load_lds_dwordx4 v[230:231], off
	s_mov_b32 m0, s58
	s_nop 0
	global_load_lds_dwordx4 v[232:233], off
	s_waitcnt vmcnt(8)
	s_waitcnt lgkmcnt(0)
	s_barrier
; #define PG8_STAGE(bufoff, gbase, voff) do { _Pragma("unroll") for (int _i = 0; _i < 2; ++_i) \
;         __builtin_amdgcn_global_load_lds((const unsigned*)((const char*)(gbase) + (voff)[_i]), (PG8_LAS unsigned*)(lds + (bufoff) + ldsw + _i * 8192), 16, 0, 0); } while (0)
; #define PG8_LDA(dst, b, h) do { _Pragma("unroll") for (int m = 0; m < 4; ++m) _Pragma("unroll") for (int k = 0; k < 2; ++k) dst[m][k] = *(const PG8_LAS bf16x8*)(lds + PG8_SA(b, h) + aoff + m * 2048 + k * 1024); } while (0)
; #define PG8_LDB(dst, b, h) do { _Pragma("unroll") for (int n = 0; n < 2; ++n) _Pragma("unroll") for (int k = 0; k < 2; ++k) dst[n][k] = *(const PG8_LAS bf16x8*)(lds + PG8_SB(b, h) + boff + n * 2048 + k * 1024); } while (0)
; #define PG8_MMA(ai, bj, At, Bt) do { __builtin_amdgcn_s_setprio(1); _Pragma("unroll") for (int m = 0; m < 4; ++m) _Pragma("unroll") for (int n = 0; n < 2; ++n) _Pragma("unroll") for (int k = 0; k < 2; ++k) \
;         acc[ai][bj][m][n] = __builtin_amdgcn_mfma_f32_16x16x32_bf16(Bt[n][k], At[m][k], acc[ai][bj][m][n], 0, 0, 0); __builtin_amdgcn_s_setprio(0); } while (0)
; #define PG8_WAIT_V(n) asm volatile("s_waitcnt vmcnt(" #n ")" ::: "memory")
; #define PG8_WAIT_L(n) asm volatile("s_waitcnt lgkmcnt(" #n ")" ::: "memory")
; #define PG8_BAR __builtin_amdgcn_s_barrier()
; #define PG8_SCHED __builtin_amdgcn_sched_barrier(0)
; template <class Epi, class Sched, bool ALIGN_EPI = false, bool SP2 = false>
; __device__ __forceinline__ void gemm_phase(PG8_LAS unsigned char* lds, const Gemm g, const Sched& S, const Epi& E, int wv) {
;     ...
;             PG8_WAIT_V(8); PG8_WAIT_L(0); PG8_BAR; PG8_MMA(1, 0, At, B0); PG8_MMA(1, 1, At, B1); PG8_BAR; PG8_SCHED;
;             PG8_LDB(B0, 1, 0); PG8_LDB(B1, 1, 1); PG8_SCHED; PG8_LDA(At, 1, 0); PG8_STAGE(PG8_SA(0, 1), a2 + hstepA, voffA);
;             PG8_WAIT_V(8); PG8_WAIT_L(0); PG8_BAR; PG8_MMA(0, 0, At, B0); PG8_MMA(0, 1, At, B1); PG8_BAR; PG8_SCHED;
	s_nop 0
	s_waitcnt lgkmcnt(0)
	v_mfma_f32_16x16x32_bf16 v[62:65], v[140:143], v[176:179], v[62:65]
	v_mfma_f32_16x16x32_bf16 v[58:61], v[152:155], v[176:179], v[58:61]
	v_mfma_f32_16x16x32_bf16 v[46:49], v[140:143], v[184:187], v[46:49]
	v_mfma_f32_16x16x32_bf16 v[42:45], v[152:155], v[184:187], v[42:45]
	v_mfma_f32_16x16x32_bf16 v[30:33], v[140:143], v[224:227], v[30:33]
	v_mfma_f32_16x16x32_bf16 v[26:29], v[152:155], v[224:227], v[26:29]
	v_mfma_f32_16x16x32_bf16 v[14:17], v[140:143], v[246:249], v[14:17]
	v_mfma_f32_16x16x32_bf16 v[10:13], v[152:155], v[246:249], v[10:13]
	v_mfma_f32_16x16x32_bf16 v[62:65], v[148:151], v[180:183], v[62:65]
	v_mfma_f32_16x16x32_bf16 v[58:61], v[156:159], v[180:183], v[58:61]
	v_mfma_f32_16x16x32_bf16 v[46:49], v[148:151], v[220:223], v[46:49]
	v_mfma_f32_16x16x32_bf16 v[42:45], v[156:159], v[220:223], v[42:45]
	v_mfma_f32_16x16x32_bf16 v[30:33], v[148:151], v[242:245], v[30:33]
	v_mfma_f32_16x16x32_bf16 v[26:29], v[156:159], v[242:245], v[26:29]
	v_mfma_f32_16x16x32_bf16 v[14:17], v[148:151], v[250:253], v[14:17]
	v_mfma_f32_16x16x32_bf16 v[10:13], v[156:159], v[250:253], v[10:13]
	s_nop 0
	s_nop 0
	v_mfma_f32_16x16x32_bf16 v[54:57], v[160:163], v[176:179], v[54:57]
	v_mfma_f32_16x16x32_bf16 v[50:53], v[168:171], v[176:179], v[50:53]
	v_mfma_f32_16x16x32_bf16 v[38:41], v[160:163], v[184:187], v[38:41]
	v_mfma_f32_16x16x32_bf16 v[34:37], v[168:171], v[184:187], v[34:37]
	v_mfma_f32_16x16x32_bf16 v[22:25], v[160:163], v[224:227], v[22:25]
	v_mfma_f32_16x16x32_bf16 v[18:21], v[168:171], v[224:227], v[18:21]
	v_mfma_f32_16x16x32_bf16 v[6:9], v[160:163], v[246:249], v[6:9]
	v_mfma_f32_16x16x32_bf16 v[2:5], v[168:171], v[246:249], v[2:5]
	v_mfma_f32_16x16x32_bf16 v[54:57], v[164:167], v[180:183], v[54:57]
	v_mfma_f32_16x16x32_bf16 v[50:53], v[172:175], v[180:183], v[50:53]
	v_mfma_f32_16x16x32_bf16 v[38:41], v[164:167], v[220:223], v[38:41]
	v_mfma_f32_16x16x32_bf16 v[34:37], v[172:175], v[220:223], v[34:37]
	v_mfma_f32_16x16x32_bf16 v[22:25], v[164:167], v[242:245], v[22:25]
	v_mfma_f32_16x16x32_bf16 v[18:21], v[172:175], v[242:245], v[18:21]
	v_mfma_f32_16x16x32_bf16 v[6:9], v[164:167], v[250:253], v[6:9]
	v_mfma_f32_16x16x32_bf16 v[2:5], v[172:175], v[250:253], v[2:5]
	s_nop 0
	s_barrier
	s_add_i32 s60, 0, 0x18000
	s_add_i32 s88, 0, 0x1c000
	v_add_u32_e32 v156, s60, v146
	v_add_u32_e32 v172, s88, v146
	ds_read_b128 v[140:143], v156
	ds_read_b128 v[148:151], v156 offset:1024
	ds_read_b128 v[152:155], v156 offset:2048
	ds_read_b128 v[156:159], v156 offset:3072
	ds_read_b128 v[160:163], v172
	ds_read_b128 v[164:167], v172 offset:1024
	ds_read_b128 v[168:171], v172 offset:2048
	ds_read_b128 v[172:175], v172 offset:3072
	s_add_u32 s22, s50, 0x40000
	s_addc_u32 s23, s51, 0
	s_mov_b32 m0, s82
	v_lshl_add_u64 v[234:235], s[22:23], 0, v[130:131]
	ds_read_b128 v[176:179], v147 offset:32768
	ds_read_b128 v[180:183], v147 offset:33792
	ds_read_b128 v[184:187], v147 offset:34816
	ds_read_b128 v[220:223], v147 offset:35840
	ds_read_b128 v[224:227], v147 offset:36864
	ds_read_b128 v[242:245], v147 offset:37888
	ds_read_b128 v[246:249], v147 offset:38912
	ds_read_b128 v[250:253], v147 offset:39936
	global_load_lds_dwordx4 v[234:235], off
	v_lshl_add_u64 v[234:235], s[22:23], 0, v[132:133]
	s_mov_b32 m0, s83
	s_nop 0
	global_load_lds_dwordx4 v[234:235], off
	s_waitcnt vmcnt(8)
	s_waitcnt lgkmcnt(0)
	s_barrier
	s_nop 0
	s_waitcnt lgkmcnt(0)
	v_mfma_f32_16x16x32_bf16 v[126:129], v[140:143], v[176:179], v[126:129]
	v_mfma_f32_16x16x32_bf16 v[122:125], v[152:155], v[176:179], v[122:125]
	v_mfma_f32_16x16x32_bf16 v[110:113], v[140:143], v[184:187], v[110:113]
	v_mfma_f32_16x16x32_bf16 v[106:109], v[152:155], v[184:187], v[106:109]
	v_mfma_f32_16x16x32_bf16 v[94:97], v[140:143], v[224:227], v[94:97]
	v_mfma_f32_16x16x32_bf16 v[90:93], v[152:155], v[224:227], v[90:93]
	v_mfma_f32_16x16x32_bf16 v[78:81], v[140:143], v[246:249], v[78:81]
	v_mfma_f32_16x16x32_bf16 v[74:77], v[152:155], v[246:249], v[74:77]
	v_mfma_f32_16x16x32_bf16 v[126:129], v[148:151], v[180:183], v[126:129]
	v_mfma_f32_16x16x32_bf16 v[122:125], v[156:159], v[180:183], v[122:125]
	v_mfma_f32_16x16x32_bf16 v[110:113], v[148:151], v[220:223], v[110:113]
	v_mfma_f32_16x16x32_bf16 v[106:109], v[156:159], v[220:223], v[106:109]
	v_mfma_f32_16x16x32_bf16 v[94:97], v[148:151], v[242:245], v[94:97]
	v_mfma_f32_16x16x32_bf16 v[90:93], v[156:159], v[242:245], v[90:93]
	v_mfma_f32_16x16x32_bf16 v[78:81], v[148:151], v[250:253], v[78:81]
	v_mfma_f32_16x16x32_bf16 v[74:77], v[156:159], v[250:253], v[74:77]
	s_nop 0
	s_nop 0
	v_mfma_f32_16x16x32_bf16 v[118:121], v[160:163], v[176:179], v[118:121]
	v_mfma_f32_16x16x32_bf16 v[114:117], v[168:171], v[176:179], v[114:117]
	v_mfma_f32_16x16x32_bf16 v[102:105], v[160:163], v[184:187], v[102:105]
	v_mfma_f32_16x16x32_bf16 v[98:101], v[168:171], v[184:187], v[98:101]
	v_mfma_f32_16x16x32_bf16 v[86:89], v[160:163], v[224:227], v[86:89]
	v_mfma_f32_16x16x32_bf16 v[82:85], v[168:171], v[224:227], v[82:85]
	v_mfma_f32_16x16x32_bf16 v[70:73], v[160:163], v[246:249], v[70:73]
	v_mfma_f32_16x16x32_bf16 v[66:69], v[168:171], v[246:249], v[66:69]
	v_mfma_f32_16x16x32_bf16 v[118:121], v[164:167], v[180:183], v[118:121]
	v_mfma_f32_16x16x32_bf16 v[114:117], v[172:175], v[180:183], v[114:117]
	v_mfma_f32_16x16x32_bf16 v[102:105], v[164:167], v[220:223], v[102:105]
	v_mfma_f32_16x16x32_bf16 v[98:101], v[172:175], v[220:223], v[98:101]
	v_mfma_f32_16x16x32_bf16 v[86:89], v[164:167], v[242:245], v[86:89]
	v_mfma_f32_16x16x32_bf16 v[82:85], v[172:175], v[242:245], v[82:85]
	v_mfma_f32_16x16x32_bf16 v[70:73], v[164:167], v[250:253], v[70:73]
	v_mfma_f32_16x16x32_bf16 v[66:69], v[172:175], v[250:253], v[66:69]
	s_nop 0
	s_barrier
; #define PG8_STAGE(bufoff, gbase, voff) do { _Pragma("unroll") for (int _i = 0; _i < 2; ++_i) \
;         __builtin_amdgcn_global_load_lds((const unsigned*)((const char*)(gbase) + (voff)[_i]), (PG8_LAS unsigned*)(lds + (bufoff) + ldsw + _i * 8192), 16, 0, 0); } while (0)
; #define PG8_LDA(dst, b, h) do { _Pragma("unroll") for (int m = 0; m < 4; ++m) _Pragma("unroll") for (int k = 0; k < 2; ++k) dst[m][k] = *(const PG8_LAS bf16x8*)(lds + PG8_SA(b, h) + aoff + m * 2048 + k * 1024); } while (0)
; #define PG8_MMA(ai, bj, At, Bt) do { __builtin_amdgcn_s_setprio(1); _Pragma("unroll") for (int m = 0; m < 4; ++m) _Pragma("unroll") for (int n = 0; n < 2; ++n) _Pragma("unroll") for (int k = 0; k < 2; ++k) \
;         acc[ai][bj][m][n] = __builtin_amdgcn_mfma_f32_16x16x32_bf16(Bt[n][k], At[m][k], acc[ai][bj][m][n], 0, 0, 0); __builtin_amdgcn_s_setprio(0); } while (0)
; #define PG8_WAIT_V(n) asm volatile("s_waitcnt vmcnt(" #n ")" ::: "memory")
; #define PG8_WAIT_L(n) asm volatile("s_waitcnt lgkmcnt(" #n ")" ::: "memory")
; #define PG8_BAR __builtin_amdgcn_s_barrier()
; #define PG8_SCHED __builtin_amdgcn_sched_barrier(0)
; template <class Epi, class Sched, bool ALIGN_EPI = false, bool SP2 = false>
; __device__ __forceinline__ void gemm_phase(PG8_LAS unsigned char* lds, const Gemm g, const Sched& S, const Epi& E, int wv) {
;     ...
;         for (int t = 0; t < nt; t += 2) {
;             const bool last = (t == nt - 2);
;     ...
;             PG8_LDA(At, 1, 1); PG8_STAGE(PG8_SB(1, 0), b3, voffB); PG8_STAGE(PG8_SB(1, 1), b3 + hstepB, voffB); PG8_STAGE(PG8_SA(1, 0), a3, voffA);
;             PG8_WAIT_V(8); PG8_WAIT_L(0); PG8_BAR; PG8_MMA(1, 0, At, B0); PG8_MMA(1, 1, At, B1); PG8_BAR; PG8_SCHED;
	s_add_i32 s22, s60, s55
	v_lshl_add_u64 v[196:197], v[196:197], 0, s[62:63]
	s_mov_b32 m0, s22
	ds_read_b128 v[176:179], v147 offset:49152
	ds_read_b128 v[180:183], v147 offset:50176
	ds_read_b128 v[184:187], v147 offset:51200
	ds_read_b128 v[220:223], v147 offset:52224
	ds_read_b128 v[224:227], v147 offset:53248
	ds_read_b128 v[242:245], v147 offset:54272
	ds_read_b128 v[246:249], v147 offset:55296
	ds_read_b128 v[250:253], v147 offset:56320
	global_load_lds_dwordx4 v[196:197], off
	s_add_i32 m0, s22, 0x2000
	s_add_u32 s2, s2, 0x40080
	v_lshl_add_u64 v[196:197], v[228:229], 0, s[62:63]
	s_addc_u32 s3, s3, 0
	s_add_i32 s22, s88, s55
	global_load_lds_dwordx4 v[196:197], off
	v_lshl_add_u64 v[196:197], s[2:3], 0, v[0:1]
	s_mov_b32 m0, s22
	s_nop 0
	global_load_lds_dwordx4 v[196:197], off
	v_lshl_add_u64 v[196:197], s[2:3], 0, v[134:135]
	s_add_i32 m0, s22, 0x2000
	s_nop 0
	global_load_lds_dwordx4 v[196:197], off
	v_lshl_add_u64 v[196:197], v[230:231], 0, s[62:63]
	s_mov_b32 m0, s91
	s_nop 0
	global_load_lds_dwordx4 v[196:197], off
	v_lshl_add_u64 v[196:197], v[232:233], 0, s[62:63]
	s_mov_b32 m0, s92
	s_nop 0
	global_load_lds_dwordx4 v[196:197], off
	s_waitcnt vmcnt(8)
	s_waitcnt lgkmcnt(0)
	s_barrier
	s_nop 0
	s_waitcnt lgkmcnt(0)
	v_mfma_f32_16x16x32_bf16 v[62:65], v[140:143], v[176:179], v[62:65]
	v_mfma_f32_16x16x32_bf16 v[58:61], v[152:155], v[176:179], v[58:61]
	v_mfma_f32_16x16x32_bf16 v[46:49], v[140:143], v[184:187], v[46:49]
	v_mfma_f32_16x16x32_bf16 v[42:45], v[152:155], v[184:187], v[42:45]
	v_mfma_f32_16x16x32_bf16 v[30:33], v[140:143], v[224:227], v[30:33]
	v_mfma_f32_16x16x32_bf16 v[26:29], v[152:155], v[224:227], v[26:29]
	v_mfma_f32_16x16x32_bf16 v[14:17], v[140:143], v[246:249], v[14:17]
	v_mfma_f32_16x16x32_bf16 v[10:13], v[152:155], v[246:249], v[10:13]
	v_mfma_f32_16x16x32_bf16 v[62:65], v[148:151], v[180:183], v[62:65]
	v_mfma_f32_16x16x32_bf16 v[58:61], v[156:159], v[180:183], v[58:61]
	v_mfma_f32_16x16x32_bf16 v[46:49], v[148:151], v[220:223], v[46:49]
	v_mfma_f32_16x16x32_bf16 v[42:45], v[156:159], v[220:223], v[42:45]
	v_mfma_f32_16x16x32_bf16 v[30:33], v[148:151], v[242:245], v[30:33]
	v_mfma_f32_16x16x32_bf16 v[26:29], v[156:159], v[242:245], v[26:29]
	v_mfma_f32_16x16x32_bf16 v[14:17], v[148:151], v[250:253], v[14:17]
	v_mfma_f32_16x16x32_bf16 v[10:13], v[156:159], v[250:253], v[10:13]
	s_nop 0
	s_nop 0
	v_mfma_f32_16x16x32_bf16 v[54:57], v[160:163], v[176:179], v[54:57]
	v_mfma_f32_16x16x32_bf16 v[50:53], v[168:171], v[176:179], v[50:53]
	v_mfma_f32_16x16x32_bf16 v[38:41], v[160:163], v[184:187], v[38:41]
	v_mfma_f32_16x16x32_bf16 v[34:37], v[168:171], v[184:187], v[34:37]
	v_mfma_f32_16x16x32_bf16 v[22:25], v[160:163], v[224:227], v[22:25]
	v_mfma_f32_16x16x32_bf16 v[18:21], v[168:171], v[224:227], v[18:21]
	v_mfma_f32_16x16x32_bf16 v[6:9], v[160:163], v[246:249], v[6:9]
	v_mfma_f32_16x16x32_bf16 v[2:5], v[168:171], v[246:249], v[2:5]
	v_mfma_f32_16x16x32_bf16 v[54:57], v[164:167], v[180:183], v[54:57]
	v_mfma_f32_16x16x32_bf16 v[50:53], v[172:175], v[180:183], v[50:53]
	v_mfma_f32_16x16x32_bf16 v[38:41], v[164:167], v[220:223], v[38:41]
	v_mfma_f32_16x16x32_bf16 v[34:37], v[172:175], v[220:223], v[34:37]
	v_mfma_f32_16x16x32_bf16 v[22:25], v[164:167], v[242:245], v[22:25]
	v_mfma_f32_16x16x32_bf16 v[18:21], v[172:175], v[242:245], v[18:21]
	v_mfma_f32_16x16x32_bf16 v[6:9], v[164:167], v[250:253], v[6:9]
	v_mfma_f32_16x16x32_bf16 v[2:5], v[172:175], v[250:253], v[2:5]
	s_nop 0
	s_barrier
	s_add_i32 vcc_lo, vcc_lo, 2
	s_add_u32 s34, s34, 0x100
	s_addc_u32 s35, s35, 0
	s_add_u32 s96, s96, 0x100
	s_addc_u32 s97, s97, 0
	s_cmp_gt_u32 vcc_lo, 13
	s_cbranch_scc0 .LBB0_663
	s_and_b64 vcc, exec, s[28:29]
	s_cbranch_vccz .LBB0_666
	s_barrier

; #define PG8_STAGE(bufoff, gbase, voff) do { _Pragma("unroll") for (int _i = 0; _i < 2; ++_i) \
;         __builtin_amdgcn_global_load_lds((const unsigned*)((const char*)(gbase) + (voff)[_i]), (PG8_LAS unsigned*)(lds + (bufoff) + ldsw + _i * 8192), 16, 0, 0); } while (0)
; #define PG8_LDA(dst, b, h) do { _Pragma("unroll") for (int m = 0; m < 4; ++m) _Pragma("unroll") for (int k = 0; k < 2; ++k) dst[m][k] = *(const PG8_LAS bf16x8*)(lds + PG8_SA(b, h) + aoff + m * 2048 + k * 1024); } while (0)
; #define PG8_LDB(dst, b, h) do { _Pragma("unroll") for (int n = 0; n < 2; ++n) _Pragma("unroll") for (int k = 0; k < 2; ++k) dst[n][k] = *(const PG8_LAS bf16x8*)(lds + PG8_SB(b, h) + boff + n * 2048 + k * 1024); } while (0)
; #define PG8_MMA(ai, bj, At, Bt) do { __builtin_amdgcn_s_setprio(1); _Pragma("unroll") for (int m = 0; m < 4; ++m) _Pragma("unroll") for (int n = 0; n < 2; ++n) _Pragma("unroll") for (int k = 0; k < 2; ++k) \
;         acc[ai][bj][m][n] = __builtin_amdgcn_mfma_f32_16x16x32_bf16(Bt[n][k], At[m][k], acc[ai][bj][m][n], 0, 0, 0); __builtin_amdgcn_s_setprio(0); } while (0)
; template <class Epi, class Sched, bool ALIGN_EPI = false, bool SP2 = false>
; __device__ __forceinline__ void gemm_phase(PG8_LAS unsigned char* lds, const Gemm g, const Sched& S, const Epi& E, int wv) {
;     ...
;         const bool has_next = S.next(ui + 1, nxt);
;         const char* nA = has_next ? (const char*)g.A + (size_t)nxt.pm * tstepA : cA; const char* nB = has_next ? (const char*)g.Bt + (size_t)nxt.pn * tstepB : cB;
; #pragma unroll 1
;         for (int t = 0; t < nt; t += 2) {
;             const bool last = (t == nt - 2);
;             const char* a1 = cA + (size_t)(t + 1) * kstep;
;             const char* a2 = last ? nA : cA + (size_t)(t + 2) * kstep; const char* b2 = last ? nB : cB + (size_t)(t + 2) * kstep;
;             const char* a3 = a2 + kstep; const char* b3 = b2 + kstep;
;             if (last && has_next) S.a_ready(nxt);
;             if constexpr (SP2) {
;             PG8_LDB(B0, 0, 0); PG8_LDB(B1, 0, 1); PG8_SCHED; PG8_LDA(At, 0, 0); PG8_STAGE(PG8_SA(1, 1), a1 + hstepA, voffA);
;             PG8_WAIT_V(8); PG8_WAIT_L(0); PG8_BAR; PG8_MMA(0, 0, At, B0); PG8_MMA(0, 1, At, B1); PG8_BAR; PG8_SCHED;
;             PG8_LDA(At, 0, 1); PG8_STAGE(PG8_SB(0, 0), b2, voffB); PG8_STAGE(PG8_SB(0, 1), b2 + hstepB, voffB); PG8_STAGE(PG8_SA(0, 0), a2, voffA);
.LBB0_888:
	s_add_u32 s7, s40, s50
	s_addc_u32 s38, s41, s51
	s_add_u32 s39, s7, 0x100
	s_addc_u32 s52, s38, 0
	s_and_b64 s[36:37], s[2:3], exec
	s_cselect_b32 s53, s45, s52
	s_cselect_b32 s52, s44, s39
	s_add_u32 s36, s34, s50
	s_addc_u32 s37, s35, s51
	s_add_u32 s36, s36, 0x100
	s_addc_u32 s37, s37, 0
	s_add_i32 s60, 0, 0x10000
	s_and_b64 s[2:3], s[2:3], exec
	s_cselect_b32 s83, s43, s37
	s_cselect_b32 s82, s24, s36
	s_add_i32 s3, 0, 0x14000
	s_add_u32 s92, s7, 0xc0080
	s_addc_u32 s93, s38, 0
	s_add_i32 s38, s60, s87
	s_add_i32 m0, s61, 0xc000
	s_add_i32 s49, s61, 0xe000
	s_add_i32 s58, s38, 0x2000
	s_add_u32 s90, s82, 0x10000
	v_add_u32_e32 v148, s60, v154
	v_add_u32_e32 v168, s3, v154
	s_addc_u32 s91, s83, 0
	s_add_i32 s39, s3, s87
	ds_read_b128 v[136:139], v148
	ds_read_b128 v[140:143], v148 offset:1024
	ds_read_b128 v[144:147], v148 offset:2048
	ds_read_b128 v[148:151], v148 offset:3072
	ds_read_b128 v[156:159], v168
	ds_read_b128 v[160:163], v168 offset:1024
	ds_read_b128 v[164:167], v168 offset:2048
	ds_read_b128 v[168:171], v168 offset:3072
	s_add_i32 s55, s39, 0x2000
	s_add_i32 s37, 0, 0x18000
	s_add_i32 s36, 0, 0x1c000
	s_add_u32 s50, s52, 0xc0000
	s_addc_u32 s51, s53, 0
	s_add_i32 vcc_hi, s37, s87
	s_add_i32 vcc_lo, vcc_hi, 0x2000
	s_add_u32 s2, s82, 0x10080
	s_addc_u32 s3, s83, 0
	s_add_i32 s88, s36, s87
	s_add_i32 s7, s88, 0x2000
	v_lshl_add_u64 v[196:197], s[92:93], 0, v[130:131]
	ds_read_b128 v[172:175], v155
	ds_read_b128 v[176:179], v155 offset:1024
	ds_read_b128 v[180:183], v155 offset:2048
	ds_read_b128 v[184:187], v155 offset:3072
	ds_read_b128 v[220:223], v155 offset:4096
	ds_read_b128 v[224:227], v155 offset:5120
	ds_read_b128 v[242:245], v155 offset:6144
	ds_read_b128 v[246:249], v155 offset:7168
	global_load_lds_dwordx4 v[196:197], off
	v_lshl_add_u64 v[196:197], s[92:93], 0, v[132:133]
	s_mov_b32 m0, s49
	s_nop 0
	global_load_lds_dwordx4 v[196:197], off
	s_waitcnt vmcnt(8)
	s_waitcnt lgkmcnt(0)
	s_barrier
	s_nop 0
	s_waitcnt lgkmcnt(0)
	v_mfma_f32_16x16x32_bf16 v[126:129], v[136:139], v[172:175], v[126:129]
	v_mfma_f32_16x16x32_bf16 v[122:125], v[144:147], v[172:175], v[122:125]
	v_mfma_f32_16x16x32_bf16 v[110:113], v[136:139], v[180:183], v[110:113]
	v_mfma_f32_16x16x32_bf16 v[106:109], v[144:147], v[180:183], v[106:109]
	v_mfma_f32_16x16x32_bf16 v[94:97], v[136:139], v[220:223], v[94:97]
	v_mfma_f32_16x16x32_bf16 v[90:93], v[144:147], v[220:223], v[90:93]
	v_mfma_f32_16x16x32_bf16 v[78:81], v[136:139], v[242:245], v[78:81]
	v_mfma_f32_16x16x32_bf16 v[74:77], v[144:147], v[242:245], v[74:77]
	v_mfma_f32_16x16x32_bf16 v[126:129], v[140:143], v[176:179], v[126:129]
	v_mfma_f32_16x16x32_bf16 v[122:125], v[148:151], v[176:179], v[122:125]
	v_mfma_f32_16x16x32_bf16 v[110:113], v[140:143], v[184:187], v[110:113]
	v_mfma_f32_16x16x32_bf16 v[106:109], v[148:151], v[184:187], v[106:109]
	v_mfma_f32_16x16x32_bf16 v[94:97], v[140:143], v[224:227], v[94:97]
	v_mfma_f32_16x16x32_bf16 v[90:93], v[148:151], v[224:227], v[90:93]
	v_mfma_f32_16x16x32_bf16 v[78:81], v[140:143], v[246:249], v[78:81]
	v_mfma_f32_16x16x32_bf16 v[74:77], v[148:151], v[246:249], v[74:77]
	s_nop 0
	s_nop 0
	v_mfma_f32_16x16x32_bf16 v[118:121], v[156:159], v[172:175], v[118:121]
	v_mfma_f32_16x16x32_bf16 v[114:117], v[164:167], v[172:175], v[114:117]
	v_mfma_f32_16x16x32_bf16 v[102:105], v[156:159], v[180:183], v[102:105]
	v_mfma_f32_16x16x32_bf16 v[98:101], v[164:167], v[180:183], v[98:101]
	v_mfma_f32_16x16x32_bf16 v[86:89], v[156:159], v[220:223], v[86:89]
	v_mfma_f32_16x16x32_bf16 v[82:85], v[164:167], v[220:223], v[82:85]
	v_mfma_f32_16x16x32_bf16 v[70:73], v[156:159], v[242:245], v[70:73]
	v_mfma_f32_16x16x32_bf16 v[66:69], v[164:167], v[242:245], v[66:69]
	v_mfma_f32_16x16x32_bf16 v[118:121], v[160:163], v[176:179], v[118:121]
	v_mfma_f32_16x16x32_bf16 v[114:117], v[168:171], v[176:179], v[114:117]
	v_mfma_f32_16x16x32_bf16 v[102:105], v[160:163], v[184:187], v[102:105]
	v_mfma_f32_16x16x32_bf16 v[98:101], v[168:171], v[184:187], v[98:101]
	v_mfma_f32_16x16x32_bf16 v[86:89], v[160:163], v[224:227], v[86:89]
	v_mfma_f32_16x16x32_bf16 v[82:85], v[168:171], v[224:227], v[82:85]
	v_mfma_f32_16x16x32_bf16 v[70:73], v[160:163], v[246:249], v[70:73]
	v_mfma_f32_16x16x32_bf16 v[66:69], v[168:171], v[246:249], v[66:69]
	s_nop 0
	s_barrier
	s_mov_b32 m0, s38
	v_lshl_add_u64 v[196:197], s[82:83], 0, v[0:1]
	ds_read_b128 v[172:175], v155 offset:16384
	ds_read_b128 v[176:179], v155 offset:17408
	ds_read_b128 v[180:183], v155 offset:18432
	ds_read_b128 v[184:187], v155 offset:19456
	ds_read_b128 v[220:223], v155 offset:20480
	ds_read_b128 v[224:227], v155 offset:21504
	ds_read_b128 v[242:245], v155 offset:22528
	ds_read_b128 v[246:249], v155 offset:23552
	global_load_lds_dwordx4 v[196:197], off
	v_lshl_add_u64 v[228:229], s[82:83], 0, v[134:135]
	s_mov_b32 m0, s58
	v_lshl_add_u64 v[230:231], s[90:91], 0, v[0:1]
	global_load_lds_dwordx4 v[228:229], off
	s_mov_b32 m0, s39
	v_lshl_add_u64 v[232:233], s[52:53], 0, v[132:133]
	global_load_lds_dwordx4 v[230:231], off
	v_lshl_add_u64 v[230:231], s[90:91], 0, v[134:135]
	s_mov_b32 m0, s55
	s_nop 0
	global_load_lds_dwordx4 v[230:231], off
	v_lshl_add_u64 v[230:231], s[52:53], 0, v[130:131]
	s_mov_b32 m0, s61
	s_nop 0
	global_load_lds_dwordx4 v[230:231], off
	s_mov_b32 m0, s94
	s_nop 0
	global_load_lds_dwordx4 v[232:233], off
	s_waitcnt vmcnt(8)
	s_waitcnt lgkmcnt(0)
	s_barrier
; #define PG8_STAGE(bufoff, gbase, voff) do { _Pragma("unroll") for (int _i = 0; _i < 2; ++_i) \
;         __builtin_amdgcn_global_load_lds((const unsigned*)((const char*)(gbase) + (voff)[_i]), (PG8_LAS unsigned*)(lds + (bufoff) + ldsw + _i * 8192), 16, 0, 0); } while (0)
; #define PG8_LDA(dst, b, h) do { _Pragma("unroll") for (int m = 0; m < 4; ++m) _Pragma("unroll") for (int k = 0; k < 2; ++k) dst[m][k] = *(const PG8_LAS bf16x8*)(lds + PG8_SA(b, h) + aoff + m * 2048 + k * 1024); } while (0)
; #define PG8_LDB(dst, b, h) do { _Pragma("unroll") for (int n = 0; n < 2; ++n) _Pragma("unroll") for (int k = 0; k < 2; ++k) dst[n][k] = *(const PG8_LAS bf16x8*)(lds + PG8_SB(b, h) + boff + n * 2048 + k * 1024); } while (0)
; #define PG8_MMA(ai, bj, At, Bt) do { __builtin_amdgcn_s_setprio(1); _Pragma("unroll") for (int m = 0; m < 4; ++m) _Pragma("unroll") for (int n = 0; n < 2; ++n) _Pragma("unroll") for (int k = 0; k < 2; ++k) \
;         acc[ai][bj][m][n] = __builtin_amdgcn_mfma_f32_16x16x32_bf16(Bt[n][k], At[m][k], acc[ai][bj][m][n], 0, 0, 0); __builtin_amdgcn_s_setprio(0); } while (0)
; #define PG8_WAIT_V(n) asm volatile("s_waitcnt vmcnt(" #n ")" ::: "memory")
; #define PG8_WAIT_L(n) asm volatile("s_waitcnt lgkmcnt(" #n ")" ::: "memory")
; #define PG8_BAR __builtin_amdgcn_s_barrier()
; #define PG8_SCHED __builtin_amdgcn_sched_barrier(0)
; template <class Epi, class Sched, bool ALIGN_EPI = false, bool SP2 = false>
; __device__ __forceinline__ void gemm_phase(PG8_LAS unsigned char* lds, const Gemm g, const Sched& S, const Epi& E, int wv) {
;     ...
;             PG8_WAIT_V(8); PG8_WAIT_L(0); PG8_BAR; PG8_MMA(1, 0, At, B0); PG8_MMA(1, 1, At, B1); PG8_BAR; PG8_SCHED;
;             PG8_LDB(B0, 1, 0); PG8_LDB(B1, 1, 1); PG8_SCHED; PG8_LDA(At, 1, 0); PG8_STAGE(PG8_SA(0, 1), a2 + hstepA, voffA);
;             PG8_WAIT_V(8); PG8_WAIT_L(0); PG8_BAR; PG8_MMA(0, 0, At, B0); PG8_MMA(0, 1, At, B1); PG8_BAR; PG8_SCHED;
	s_nop 0
	s_waitcnt lgkmcnt(0)
	v_mfma_f32_16x16x32_bf16 v[62:65], v[136:139], v[172:175], v[62:65]
	v_mfma_f32_16x16x32_bf16 v[58:61], v[144:147], v[172:175], v[58:61]
	v_mfma_f32_16x16x32_bf16 v[46:49], v[136:139], v[180:183], v[46:49]
	v_mfma_f32_16x16x32_bf16 v[42:45], v[144:147], v[180:183], v[42:45]
	v_mfma_f32_16x16x32_bf16 v[30:33], v[136:139], v[220:223], v[30:33]
	v_mfma_f32_16x16x32_bf16 v[26:29], v[144:147], v[220:223], v[26:29]
	v_mfma_f32_16x16x32_bf16 v[14:17], v[136:139], v[242:245], v[14:17]
	v_mfma_f32_16x16x32_bf16 v[10:13], v[144:147], v[242:245], v[10:13]
	v_mfma_f32_16x16x32_bf16 v[62:65], v[140:143], v[176:179], v[62:65]
	v_mfma_f32_16x16x32_bf16 v[58:61], v[148:151], v[176:179], v[58:61]
	v_mfma_f32_16x16x32_bf16 v[46:49], v[140:143], v[184:187], v[46:49]
	v_mfma_f32_16x16x32_bf16 v[42:45], v[148:151], v[184:187], v[42:45]
	v_mfma_f32_16x16x32_bf16 v[30:33], v[140:143], v[224:227], v[30:33]
	v_mfma_f32_16x16x32_bf16 v[26:29], v[148:151], v[224:227], v[26:29]
	v_mfma_f32_16x16x32_bf16 v[14:17], v[140:143], v[246:249], v[14:17]
	v_mfma_f32_16x16x32_bf16 v[10:13], v[148:151], v[246:249], v[10:13]
	s_nop 0
	s_nop 0
	v_mfma_f32_16x16x32_bf16 v[54:57], v[156:159], v[172:175], v[54:57]
	v_mfma_f32_16x16x32_bf16 v[50:53], v[164:167], v[172:175], v[50:53]
	v_mfma_f32_16x16x32_bf16 v[38:41], v[156:159], v[180:183], v[38:41]
	v_mfma_f32_16x16x32_bf16 v[34:37], v[164:167], v[180:183], v[34:37]
	v_mfma_f32_16x16x32_bf16 v[22:25], v[156:159], v[220:223], v[22:25]
	v_mfma_f32_16x16x32_bf16 v[18:21], v[164:167], v[220:223], v[18:21]
	v_mfma_f32_16x16x32_bf16 v[6:9], v[156:159], v[242:245], v[6:9]
	v_mfma_f32_16x16x32_bf16 v[2:5], v[164:167], v[242:245], v[2:5]
	v_mfma_f32_16x16x32_bf16 v[54:57], v[160:163], v[176:179], v[54:57]
	v_mfma_f32_16x16x32_bf16 v[50:53], v[168:171], v[176:179], v[50:53]
	v_mfma_f32_16x16x32_bf16 v[38:41], v[160:163], v[184:187], v[38:41]
	v_mfma_f32_16x16x32_bf16 v[34:37], v[168:171], v[184:187], v[34:37]
	v_mfma_f32_16x16x32_bf16 v[22:25], v[160:163], v[224:227], v[22:25]
	v_mfma_f32_16x16x32_bf16 v[18:21], v[168:171], v[224:227], v[18:21]
	v_mfma_f32_16x16x32_bf16 v[6:9], v[160:163], v[246:249], v[6:9]
	v_mfma_f32_16x16x32_bf16 v[2:5], v[168:171], v[246:249], v[2:5]
	s_nop 0
	s_barrier
	v_add_u32_e32 v148, s37, v154
	v_add_u32_e32 v168, s36, v154
	ds_read_b128 v[136:139], v148
	ds_read_b128 v[140:143], v148 offset:1024
	ds_read_b128 v[144:147], v148 offset:2048
	ds_read_b128 v[148:151], v148 offset:3072
	ds_read_b128 v[156:159], v168
	ds_read_b128 v[160:163], v168 offset:1024
	ds_read_b128 v[164:167], v168 offset:2048
	ds_read_b128 v[168:171], v168 offset:3072
	s_mov_b32 m0, s95
	v_lshl_add_u64 v[234:235], s[50:51], 0, v[130:131]
	ds_read_b128 v[172:175], v155 offset:32768
	ds_read_b128 v[176:179], v155 offset:33792
	ds_read_b128 v[180:183], v155 offset:34816
	ds_read_b128 v[184:187], v155 offset:35840
	ds_read_b128 v[220:223], v155 offset:36864
	ds_read_b128 v[224:227], v155 offset:37888
	ds_read_b128 v[242:245], v155 offset:38912
	ds_read_b128 v[246:249], v155 offset:39936
	global_load_lds_dwordx4 v[234:235], off
	v_lshl_add_u64 v[234:235], s[50:51], 0, v[132:133]
	s_mov_b32 m0, s97
	s_nop 0
	global_load_lds_dwordx4 v[234:235], off
	s_waitcnt vmcnt(8)
	s_waitcnt lgkmcnt(0)
	s_barrier
	s_nop 0
	s_waitcnt lgkmcnt(0)
	v_mfma_f32_16x16x32_bf16 v[126:129], v[136:139], v[172:175], v[126:129]
	v_mfma_f32_16x16x32_bf16 v[122:125], v[144:147], v[172:175], v[122:125]
	v_mfma_f32_16x16x32_bf16 v[110:113], v[136:139], v[180:183], v[110:113]
	v_mfma_f32_16x16x32_bf16 v[106:109], v[144:147], v[180:183], v[106:109]
	v_mfma_f32_16x16x32_bf16 v[94:97], v[136:139], v[220:223], v[94:97]
	v_mfma_f32_16x16x32_bf16 v[90:93], v[144:147], v[220:223], v[90:93]
	v_mfma_f32_16x16x32_bf16 v[78:81], v[136:139], v[242:245], v[78:81]
	v_mfma_f32_16x16x32_bf16 v[74:77], v[144:147], v[242:245], v[74:77]
	v_mfma_f32_16x16x32_bf16 v[126:129], v[140:143], v[176:179], v[126:129]
	v_mfma_f32_16x16x32_bf16 v[122:125], v[148:151], v[176:179], v[122:125]
	v_mfma_f32_16x16x32_bf16 v[110:113], v[140:143], v[184:187], v[110:113]
	v_mfma_f32_16x16x32_bf16 v[106:109], v[148:151], v[184:187], v[106:109]
	v_mfma_f32_16x16x32_bf16 v[94:97], v[140:143], v[224:227], v[94:97]
	v_mfma_f32_16x16x32_bf16 v[90:93], v[148:151], v[224:227], v[90:93]
	v_mfma_f32_16x16x32_bf16 v[78:81], v[140:143], v[246:249], v[78:81]
	v_mfma_f32_16x16x32_bf16 v[74:77], v[148:151], v[246:249], v[74:77]
	s_nop 0
	s_nop 0
	v_mfma_f32_16x16x32_bf16 v[118:121], v[156:159], v[172:175], v[118:121]
	v_mfma_f32_16x16x32_bf16 v[114:117], v[164:167], v[172:175], v[114:117]
	v_mfma_f32_16x16x32_bf16 v[102:105], v[156:159], v[180:183], v[102:105]
	v_mfma_f32_16x16x32_bf16 v[98:101], v[164:167], v[180:183], v[98:101]
	v_mfma_f32_16x16x32_bf16 v[86:89], v[156:159], v[220:223], v[86:89]
	v_mfma_f32_16x16x32_bf16 v[82:85], v[164:167], v[220:223], v[82:85]
	v_mfma_f32_16x16x32_bf16 v[70:73], v[156:159], v[242:245], v[70:73]
	v_mfma_f32_16x16x32_bf16 v[66:69], v[164:167], v[242:245], v[66:69]
	v_mfma_f32_16x16x32_bf16 v[118:121], v[160:163], v[176:179], v[118:121]
	v_mfma_f32_16x16x32_bf16 v[114:117], v[168:171], v[176:179], v[114:117]
	v_mfma_f32_16x16x32_bf16 v[102:105], v[160:163], v[184:187], v[102:105]
	v_mfma_f32_16x16x32_bf16 v[98:101], v[168:171], v[184:187], v[98:101]
	v_mfma_f32_16x16x32_bf16 v[86:89], v[160:163], v[224:227], v[86:89]
	v_mfma_f32_16x16x32_bf16 v[82:85], v[168:171], v[224:227], v[82:85]
	v_mfma_f32_16x16x32_bf16 v[70:73], v[160:163], v[246:249], v[70:73]
	v_mfma_f32_16x16x32_bf16 v[66:69], v[168:171], v[246:249], v[66:69]
	s_nop 0
	s_barrier
; #define PG8_STAGE(bufoff, gbase, voff) do { _Pragma("unroll") for (int _i = 0; _i < 2; ++_i) \
;         __builtin_amdgcn_global_load_lds((const unsigned*)((const char*)(gbase) + (voff)[_i]), (PG8_LAS unsigned*)(lds + (bufoff) + ldsw + _i * 8192), 16, 0, 0); } while (0)
; #define PG8_LDA(dst, b, h) do { _Pragma("unroll") for (int m = 0; m < 4; ++m) _Pragma("unroll") for (int k = 0; k < 2; ++k) dst[m][k] = *(const PG8_LAS bf16x8*)(lds + PG8_SA(b, h) + aoff + m * 2048 + k * 1024); } while (0)
; #define PG8_MMA(ai, bj, At, Bt) do { __builtin_amdgcn_s_setprio(1); _Pragma("unroll") for (int m = 0; m < 4; ++m) _Pragma("unroll") for (int n = 0; n < 2; ++n) _Pragma("unroll") for (int k = 0; k < 2; ++k) \
;         acc[ai][bj][m][n] = __builtin_amdgcn_mfma_f32_16x16x32_bf16(Bt[n][k], At[m][k], acc[ai][bj][m][n], 0, 0, 0); __builtin_amdgcn_s_setprio(0); } while (0)
; #define PG8_WAIT_V(n) asm volatile("s_waitcnt vmcnt(" #n ")" ::: "memory")
; #define PG8_WAIT_L(n) asm volatile("s_waitcnt lgkmcnt(" #n ")" ::: "memory")
; #define PG8_BAR __builtin_amdgcn_s_barrier()
; #define PG8_SCHED __builtin_amdgcn_sched_barrier(0)
; template <class Epi, class Sched, bool ALIGN_EPI = false, bool SP2 = false>
; __device__ __forceinline__ void gemm_phase(PG8_LAS unsigned char* lds, const Gemm g, const Sched& S, const Epi& E, int wv) {
;     ...
;         for (int t = 0; t < nt; t += 2) {
;             const bool last = (t == nt - 2);
;     ...
;             PG8_LDA(At, 1, 1); PG8_STAGE(PG8_SB(1, 0), b3, voffB); PG8_STAGE(PG8_SB(1, 1), b3 + hstepB, voffB); PG8_STAGE(PG8_SA(1, 0), a3, voffA);
;             PG8_WAIT_V(8); PG8_WAIT_L(0); PG8_BAR; PG8_MMA(1, 0, At, B0); PG8_MMA(1, 1, At, B1); PG8_BAR; PG8_SCHED;
	s_mov_b32 m0, vcc_hi
	v_lshl_add_u64 v[196:197], v[196:197], 0, s[62:63]
	ds_read_b128 v[172:175], v155 offset:49152
	ds_read_b128 v[176:179], v155 offset:50176
	ds_read_b128 v[180:183], v155 offset:51200
	ds_read_b128 v[184:187], v155 offset:52224
	ds_read_b128 v[220:223], v155 offset:53248
	ds_read_b128 v[224:227], v155 offset:54272
	ds_read_b128 v[242:245], v155 offset:55296
	ds_read_b128 v[246:249], v155 offset:56320
	global_load_lds_dwordx4 v[196:197], off
	v_lshl_add_u64 v[196:197], v[228:229], 0, s[62:63]
	s_mov_b32 m0, vcc_lo
	s_nop 0
	global_load_lds_dwordx4 v[196:197], off
	v_lshl_add_u64 v[196:197], s[2:3], 0, v[0:1]
	s_mov_b32 m0, s88
	s_nop 0
	global_load_lds_dwordx4 v[196:197], off
	v_lshl_add_u64 v[196:197], s[2:3], 0, v[134:135]
	s_mov_b32 m0, s7
	s_nop 0
	global_load_lds_dwordx4 v[196:197], off
	v_lshl_add_u64 v[196:197], v[230:231], 0, s[62:63]
	s_mov_b32 m0, s25
	s_nop 0
	global_load_lds_dwordx4 v[196:197], off
	v_lshl_add_u64 v[196:197], v[232:233], 0, s[62:63]
	s_mov_b32 m0, s13
	s_nop 0
	global_load_lds_dwordx4 v[196:197], off
	s_waitcnt vmcnt(8)
	s_waitcnt lgkmcnt(0)
	s_barrier
	s_nop 0
	s_waitcnt lgkmcnt(0)
	v_mfma_f32_16x16x32_bf16 v[62:65], v[136:139], v[172:175], v[62:65]
	v_mfma_f32_16x16x32_bf16 v[58:61], v[144:147], v[172:175], v[58:61]
	v_mfma_f32_16x16x32_bf16 v[46:49], v[136:139], v[180:183], v[46:49]
	v_mfma_f32_16x16x32_bf16 v[42:45], v[144:147], v[180:183], v[42:45]
	v_mfma_f32_16x16x32_bf16 v[30:33], v[136:139], v[220:223], v[30:33]
	v_mfma_f32_16x16x32_bf16 v[26:29], v[144:147], v[220:223], v[26:29]
	v_mfma_f32_16x16x32_bf16 v[14:17], v[136:139], v[242:245], v[14:17]
	v_mfma_f32_16x16x32_bf16 v[10:13], v[144:147], v[242:245], v[10:13]
	v_mfma_f32_16x16x32_bf16 v[62:65], v[140:143], v[176:179], v[62:65]
	v_mfma_f32_16x16x32_bf16 v[58:61], v[148:151], v[176:179], v[58:61]
	v_mfma_f32_16x16x32_bf16 v[46:49], v[140:143], v[184:187], v[46:49]
	v_mfma_f32_16x16x32_bf16 v[42:45], v[148:151], v[184:187], v[42:45]
	v_mfma_f32_16x16x32_bf16 v[30:33], v[140:143], v[224:227], v[30:33]
	v_mfma_f32_16x16x32_bf16 v[26:29], v[148:151], v[224:227], v[26:29]
	v_mfma_f32_16x16x32_bf16 v[14:17], v[140:143], v[246:249], v[14:17]
	v_mfma_f32_16x16x32_bf16 v[10:13], v[148:151], v[246:249], v[10:13]
	s_nop 0
	s_nop 0
	v_mfma_f32_16x16x32_bf16 v[54:57], v[156:159], v[172:175], v[54:57]
	v_mfma_f32_16x16x32_bf16 v[50:53], v[164:167], v[172:175], v[50:53]
	v_mfma_f32_16x16x32_bf16 v[38:41], v[156:159], v[180:183], v[38:41]
	v_mfma_f32_16x16x32_bf16 v[34:37], v[164:167], v[180:183], v[34:37]
	v_mfma_f32_16x16x32_bf16 v[22:25], v[156:159], v[220:223], v[22:25]
	v_mfma_f32_16x16x32_bf16 v[18:21], v[164:167], v[220:223], v[18:21]
	v_mfma_f32_16x16x32_bf16 v[6:9], v[156:159], v[242:245], v[6:9]
	v_mfma_f32_16x16x32_bf16 v[2:5], v[164:167], v[242:245], v[2:5]
	v_mfma_f32_16x16x32_bf16 v[54:57], v[160:163], v[176:179], v[54:57]
	v_mfma_f32_16x16x32_bf16 v[50:53], v[168:171], v[176:179], v[50:53]
	v_mfma_f32_16x16x32_bf16 v[38:41], v[160:163], v[184:187], v[38:41]
	v_mfma_f32_16x16x32_bf16 v[34:37], v[168:171], v[184:187], v[34:37]
	v_mfma_f32_16x16x32_bf16 v[22:25], v[160:163], v[224:227], v[22:25]
	v_mfma_f32_16x16x32_bf16 v[18:21], v[168:171], v[224:227], v[18:21]
	v_mfma_f32_16x16x32_bf16 v[6:9], v[160:163], v[246:249], v[6:9]
	v_mfma_f32_16x16x32_bf16 v[2:5], v[168:171], v[246:249], v[2:5]
	s_nop 0
	s_barrier
	s_andn2_b64 vcc, exec, s[18:19]
	s_mov_b64 s[2:3], -1
	s_mov_b64 s[18:19], 0
	s_mov_b64 s[50:51], 0x100
	s_cbranch_vccz .LBB0_888
	v_readlane_b32 s2, v255, 8
	v_readlane_b32 s3, v255, 9
	s_and_b64 vcc, exec, s[2:3]
	s_cbranch_vccz .LBB0_891
	s_barrier

; #define PG8_STAGE(bufoff, gbase, voff) do { _Pragma("unroll") for (int _i = 0; _i < 2; ++_i) \
;         __builtin_amdgcn_global_load_lds((const unsigned*)((const char*)(gbase) + (voff)[_i]), (PG8_LAS unsigned*)(lds + (bufoff) + ldsw + _i * 8192), 16, 0, 0); } while (0)
; #define PG8_LDA(dst, b, h) do { _Pragma("unroll") for (int m = 0; m < 4; ++m) _Pragma("unroll") for (int k = 0; k < 2; ++k) dst[m][k] = *(const PG8_LAS bf16x8*)(lds + PG8_SA(b, h) + aoff + m * 2048 + k * 1024); } while (0)
; #define PG8_LDB(dst, b, h) do { _Pragma("unroll") for (int n = 0; n < 2; ++n) _Pragma("unroll") for (int k = 0; k < 2; ++k) dst[n][k] = *(const PG8_LAS bf16x8*)(lds + PG8_SB(b, h) + boff + n * 2048 + k * 1024); } while (0)
; #define PG8_MMA(ai, bj, At, Bt) do { __builtin_amdgcn_s_setprio(1); _Pragma("unroll") for (int m = 0; m < 4; ++m) _Pragma("unroll") for (int n = 0; n < 2; ++n) _Pragma("unroll") for (int k = 0; k < 2; ++k) \
;         acc[ai][bj][m][n] = __builtin_amdgcn_mfma_f32_16x16x32_bf16(Bt[n][k], At[m][k], acc[ai][bj][m][n], 0, 0, 0); __builtin_amdgcn_s_setprio(0); } while (0)
; template <class Epi, class Sched, bool ALIGN_EPI = false, bool SP2 = false>
; __device__ __forceinline__ void gemm_phase(PG8_LAS unsigned char* lds, const Gemm g, const Sched& S, const Epi& E, int wv) {
;     ...
;         const bool has_next = S.next(ui + 1, nxt);
;         const char* nA = has_next ? (const char*)g.A + (size_t)nxt.pm * tstepA : cA; const char* nB = has_next ? (const char*)g.Bt + (size_t)nxt.pn * tstepB : cB;
; #pragma unroll 1
;         for (int t = 0; t < nt; t += 2) {
;             const bool last = (t == nt - 2);
;             const char* a1 = cA + (size_t)(t + 1) * kstep;
;             const char* a2 = last ? nA : cA + (size_t)(t + 2) * kstep; const char* b2 = last ? nB : cB + (size_t)(t + 2) * kstep;
;             const char* a3 = a2 + kstep; const char* b3 = b2 + kstep;
;             if (last && has_next) S.a_ready(nxt);
;             if constexpr (SP2) {
;             PG8_LDB(B0, 0, 0); PG8_LDB(B1, 0, 1); PG8_SCHED; PG8_LDA(At, 0, 0); PG8_STAGE(PG8_SA(1, 1), a1 + hstepA, voffA);
;             PG8_WAIT_V(8); PG8_WAIT_L(0); PG8_BAR; PG8_MMA(0, 0, At, B0); PG8_MMA(0, 1, At, B1); PG8_BAR; PG8_SCHED;
;             PG8_LDA(At, 0, 1); PG8_STAGE(PG8_SB(0, 0), b2, voffB); PG8_STAGE(PG8_SB(0, 1), b2 + hstepB, voffB); PG8_STAGE(PG8_SA(0, 0), a2, voffA);
.LBB0_1271:
	s_add_u32 s13, s34, s42
	s_addc_u32 s27, s35, s43
	s_add_u32 s48, s13, 0x100
	s_addc_u32 s49, s27, 0
	s_and_b64 s[22:23], s[2:3], exec
	s_cselect_b32 s53, s95, s49
	s_cselect_b32 s52, s94, s48
	s_add_u32 s22, s40, s42
	s_addc_u32 s23, s41, s43
	s_add_u32 s22, s22, 0x100
	s_addc_u32 s23, s23, 0
	s_add_i32 s60, 0, 0x10000
	s_and_b64 s[2:3], s[2:3], exec
	s_cselect_b32 s83, s51, s23
	s_cselect_b32 s82, s44, s22
	s_add_i32 s3, 0, 0x14000
	s_add_u32 s92, s13, 0xc0080
	s_addc_u32 s93, s27, 0
	s_add_i32 s48, s60, s28
	s_add_i32 m0, s29, 0xc000
	s_add_i32 s61, s29, 0xe000
	s_add_i32 s13, s48, 0x2000
	v_add_u32_e32 v144, s60, v148
	s_add_u32 s90, s82, 0x10000
	ds_read_b128 v[136:139], v144
	ds_read_b128 v[140:143], v144 offset:1024
	ds_read_b128 v[150:153], v144 offset:2048
	ds_read_b128 v[154:157], v144 offset:3072
	v_add_u32_e32 v144, s3, v148
	s_addc_u32 s91, s83, 0
	s_add_i32 s49, s3, s28
	ds_read_b128 v[158:161], v144
	ds_read_b128 v[162:165], v144 offset:1024
	ds_read_b128 v[166:169], v144 offset:2048
	ds_read_b128 v[170:173], v144 offset:3072
	s_add_i32 s27, s49, 0x2000
	s_add_i32 s23, 0, 0x18000
	s_add_i32 s22, 0, 0x1c000
	s_add_u32 s42, s52, 0xc0000
	s_addc_u32 s43, s53, 0
	s_add_i32 vcc_hi, s23, s28
	s_add_i32 vcc_lo, vcc_hi, 0x2000
	s_add_u32 s2, s82, 0x10080
	s_addc_u32 s3, s83, 0
	s_add_i32 s88, s22, s28
	s_add_i32 s60, s88, 0x2000
	v_lshl_add_u64 v[144:145], s[92:93], 0, v[0:1]
	ds_read_b128 v[174:177], v149
	ds_read_b128 v[178:181], v149 offset:1024
	ds_read_b128 v[182:185], v149 offset:2048
	ds_read_b128 v[220:223], v149 offset:3072
	ds_read_b128 v[224:227], v149 offset:4096
	ds_read_b128 v[242:245], v149 offset:5120
	ds_read_b128 v[246:249], v149 offset:6144
	ds_read_b128 v[250:253], v149 offset:7168
	global_load_lds_dwordx4 v[144:145], off
	v_lshl_add_u64 v[144:145], s[92:93], 0, v[132:133]
	s_mov_b32 m0, s61
	s_nop 0
	global_load_lds_dwordx4 v[144:145], off
	s_waitcnt vmcnt(8)
	s_waitcnt lgkmcnt(0)
	s_barrier
	s_nop 0
	s_waitcnt lgkmcnt(0)
	v_mfma_f32_16x16x32_bf16 v[126:129], v[136:139], v[174:177], v[126:129]
	v_mfma_f32_16x16x32_bf16 v[122:125], v[150:153], v[174:177], v[122:125]
	v_mfma_f32_16x16x32_bf16 v[110:113], v[136:139], v[182:185], v[110:113]
	v_mfma_f32_16x16x32_bf16 v[106:109], v[150:153], v[182:185], v[106:109]
	v_mfma_f32_16x16x32_bf16 v[94:97], v[136:139], v[224:227], v[94:97]
	v_mfma_f32_16x16x32_bf16 v[90:93], v[150:153], v[224:227], v[90:93]
	v_mfma_f32_16x16x32_bf16 v[78:81], v[136:139], v[246:249], v[78:81]
	v_mfma_f32_16x16x32_bf16 v[74:77], v[150:153], v[246:249], v[74:77]
	v_mfma_f32_16x16x32_bf16 v[126:129], v[140:143], v[178:181], v[126:129]
	v_mfma_f32_16x16x32_bf16 v[122:125], v[154:157], v[178:181], v[122:125]
	v_mfma_f32_16x16x32_bf16 v[110:113], v[140:143], v[220:223], v[110:113]
	v_mfma_f32_16x16x32_bf16 v[106:109], v[154:157], v[220:223], v[106:109]
	v_mfma_f32_16x16x32_bf16 v[94:97], v[140:143], v[242:245], v[94:97]
	v_mfma_f32_16x16x32_bf16 v[90:93], v[154:157], v[242:245], v[90:93]
	v_mfma_f32_16x16x32_bf16 v[78:81], v[140:143], v[250:253], v[78:81]
	v_mfma_f32_16x16x32_bf16 v[74:77], v[154:157], v[250:253], v[74:77]
	s_nop 0
	s_nop 0
	v_mfma_f32_16x16x32_bf16 v[118:121], v[158:161], v[174:177], v[118:121]
	v_mfma_f32_16x16x32_bf16 v[114:117], v[166:169], v[174:177], v[114:117]
	v_mfma_f32_16x16x32_bf16 v[102:105], v[158:161], v[182:185], v[102:105]
	v_mfma_f32_16x16x32_bf16 v[98:101], v[166:169], v[182:185], v[98:101]
	v_mfma_f32_16x16x32_bf16 v[86:89], v[158:161], v[224:227], v[86:89]
	v_mfma_f32_16x16x32_bf16 v[82:85], v[166:169], v[224:227], v[82:85]
	v_mfma_f32_16x16x32_bf16 v[70:73], v[158:161], v[246:249], v[70:73]
	v_mfma_f32_16x16x32_bf16 v[66:69], v[166:169], v[246:249], v[66:69]
	v_mfma_f32_16x16x32_bf16 v[118:121], v[162:165], v[178:181], v[118:121]
	v_mfma_f32_16x16x32_bf16 v[114:117], v[170:173], v[178:181], v[114:117]
	v_mfma_f32_16x16x32_bf16 v[102:105], v[162:165], v[220:223], v[102:105]
	v_mfma_f32_16x16x32_bf16 v[98:101], v[170:173], v[220:223], v[98:101]
	v_mfma_f32_16x16x32_bf16 v[86:89], v[162:165], v[242:245], v[86:89]
	v_mfma_f32_16x16x32_bf16 v[82:85], v[170:173], v[242:245], v[82:85]
	v_mfma_f32_16x16x32_bf16 v[70:73], v[162:165], v[250:253], v[70:73]
	v_mfma_f32_16x16x32_bf16 v[66:69], v[170:173], v[250:253], v[66:69]
	s_nop 0
	s_barrier
	s_mov_b32 m0, s48
	v_lshl_add_u64 v[144:145], s[82:83], 0, v[130:131]
	ds_read_b128 v[174:177], v149 offset:16384
	ds_read_b128 v[178:181], v149 offset:17408
	ds_read_b128 v[182:185], v149 offset:18432
	ds_read_b128 v[220:223], v149 offset:19456
	ds_read_b128 v[224:227], v149 offset:20480
	ds_read_b128 v[242:245], v149 offset:21504
	ds_read_b128 v[246:249], v149 offset:22528
	ds_read_b128 v[250:253], v149 offset:23552
	global_load_lds_dwordx4 v[144:145], off
	v_lshl_add_u64 v[186:187], s[82:83], 0, v[134:135]
	s_mov_b32 m0, s13
	v_lshl_add_u64 v[196:197], s[90:91], 0, v[130:131]
	global_load_lds_dwordx4 v[186:187], off
	s_mov_b32 m0, s49
	v_lshl_add_u64 v[228:229], s[52:53], 0, v[132:133]
	global_load_lds_dwordx4 v[196:197], off
	v_lshl_add_u64 v[196:197], s[90:91], 0, v[134:135]
	s_mov_b32 m0, s27
	s_nop 0
	global_load_lds_dwordx4 v[196:197], off
	v_lshl_add_u64 v[196:197], s[52:53], 0, v[0:1]
	s_mov_b32 m0, s29
	s_nop 0
	global_load_lds_dwordx4 v[196:197], off
	s_mov_b32 m0, s46
	s_nop 0
	global_load_lds_dwordx4 v[228:229], off
	s_waitcnt vmcnt(8)
	s_waitcnt lgkmcnt(0)
	s_barrier
; #define PG8_STAGE(bufoff, gbase, voff) do { _Pragma("unroll") for (int _i = 0; _i < 2; ++_i) \
;         __builtin_amdgcn_global_load_lds((const unsigned*)((const char*)(gbase) + (voff)[_i]), (PG8_LAS unsigned*)(lds + (bufoff) + ldsw + _i * 8192), 16, 0, 0); } while (0)
; #define PG8_LDA(dst, b, h) do { _Pragma("unroll") for (int m = 0; m < 4; ++m) _Pragma("unroll") for (int k = 0; k < 2; ++k) dst[m][k] = *(const PG8_LAS bf16x8*)(lds + PG8_SA(b, h) + aoff + m * 2048 + k * 1024); } while (0)
; #define PG8_LDB(dst, b, h) do { _Pragma("unroll") for (int n = 0; n < 2; ++n) _Pragma("unroll") for (int k = 0; k < 2; ++k) dst[n][k] = *(const PG8_LAS bf16x8*)(lds + PG8_SB(b, h) + boff + n * 2048 + k * 1024); } while (0)
; #define PG8_MMA(ai, bj, At, Bt) do { __builtin_amdgcn_s_setprio(1); _Pragma("unroll") for (int m = 0; m < 4; ++m) _Pragma("unroll") for (int n = 0; n < 2; ++n) _Pragma("unroll") for (int k = 0; k < 2; ++k) \
;         acc[ai][bj][m][n] = __builtin_amdgcn_mfma_f32_16x16x32_bf16(Bt[n][k], At[m][k], acc[ai][bj][m][n], 0, 0, 0); __builtin_amdgcn_s_setprio(0); } while (0)
; #define PG8_WAIT_V(n) asm volatile("s_waitcnt vmcnt(" #n ")" ::: "memory")
; #define PG8_WAIT_L(n) asm volatile("s_waitcnt lgkmcnt(" #n ")" ::: "memory")
; #define PG8_BAR __builtin_amdgcn_s_barrier()
; #define PG8_SCHED __builtin_amdgcn_sched_barrier(0)
; template <class Epi, class Sched, bool ALIGN_EPI = false, bool SP2 = false>
; __device__ __forceinline__ void gemm_phase(PG8_LAS unsigned char* lds, const Gemm g, const Sched& S, const Epi& E, int wv) {
;     ...
;             PG8_WAIT_V(8); PG8_WAIT_L(0); PG8_BAR; PG8_MMA(1, 0, At, B0); PG8_MMA(1, 1, At, B1); PG8_BAR; PG8_SCHED;
;             PG8_LDB(B0, 1, 0); PG8_LDB(B1, 1, 1); PG8_SCHED; PG8_LDA(At, 1, 0); PG8_STAGE(PG8_SA(0, 1), a2 + hstepA, voffA);
;             PG8_WAIT_V(8); PG8_WAIT_L(0); PG8_BAR; PG8_MMA(0, 0, At, B0); PG8_MMA(0, 1, At, B1); PG8_BAR; PG8_SCHED;
	s_nop 0
	s_waitcnt lgkmcnt(0)
	v_mfma_f32_16x16x32_bf16 v[62:65], v[136:139], v[174:177], v[62:65]
	v_mfma_f32_16x16x32_bf16 v[58:61], v[150:153], v[174:177], v[58:61]
	v_mfma_f32_16x16x32_bf16 v[46:49], v[136:139], v[182:185], v[46:49]
	v_mfma_f32_16x16x32_bf16 v[42:45], v[150:153], v[182:185], v[42:45]
	v_mfma_f32_16x16x32_bf16 v[30:33], v[136:139], v[224:227], v[30:33]
	v_mfma_f32_16x16x32_bf16 v[26:29], v[150:153], v[224:227], v[26:29]
	v_mfma_f32_16x16x32_bf16 v[14:17], v[136:139], v[246:249], v[14:17]
	v_mfma_f32_16x16x32_bf16 v[10:13], v[150:153], v[246:249], v[10:13]
	v_mfma_f32_16x16x32_bf16 v[62:65], v[140:143], v[178:181], v[62:65]
	v_mfma_f32_16x16x32_bf16 v[58:61], v[154:157], v[178:181], v[58:61]
	v_mfma_f32_16x16x32_bf16 v[46:49], v[140:143], v[220:223], v[46:49]
	v_mfma_f32_16x16x32_bf16 v[42:45], v[154:157], v[220:223], v[42:45]
	v_mfma_f32_16x16x32_bf16 v[30:33], v[140:143], v[242:245], v[30:33]
	v_mfma_f32_16x16x32_bf16 v[26:29], v[154:157], v[242:245], v[26:29]
	v_mfma_f32_16x16x32_bf16 v[14:17], v[140:143], v[250:253], v[14:17]
	v_mfma_f32_16x16x32_bf16 v[10:13], v[154:157], v[250:253], v[10:13]
	s_nop 0
	s_nop 0
	v_mfma_f32_16x16x32_bf16 v[54:57], v[158:161], v[174:177], v[54:57]
	v_mfma_f32_16x16x32_bf16 v[50:53], v[166:169], v[174:177], v[50:53]
	v_mfma_f32_16x16x32_bf16 v[38:41], v[158:161], v[182:185], v[38:41]
	v_mfma_f32_16x16x32_bf16 v[34:37], v[166:169], v[182:185], v[34:37]
	v_mfma_f32_16x16x32_bf16 v[22:25], v[158:161], v[224:227], v[22:25]
	v_mfma_f32_16x16x32_bf16 v[18:21], v[166:169], v[224:227], v[18:21]
	v_mfma_f32_16x16x32_bf16 v[6:9], v[158:161], v[246:249], v[6:9]
	v_mfma_f32_16x16x32_bf16 v[2:5], v[166:169], v[246:249], v[2:5]
	v_mfma_f32_16x16x32_bf16 v[54:57], v[162:165], v[178:181], v[54:57]
	v_mfma_f32_16x16x32_bf16 v[50:53], v[170:173], v[178:181], v[50:53]
	v_mfma_f32_16x16x32_bf16 v[38:41], v[162:165], v[220:223], v[38:41]
	v_mfma_f32_16x16x32_bf16 v[34:37], v[170:173], v[220:223], v[34:37]
	v_mfma_f32_16x16x32_bf16 v[22:25], v[162:165], v[242:245], v[22:25]
	v_mfma_f32_16x16x32_bf16 v[18:21], v[170:173], v[242:245], v[18:21]
	v_mfma_f32_16x16x32_bf16 v[6:9], v[162:165], v[250:253], v[6:9]
	v_mfma_f32_16x16x32_bf16 v[2:5], v[170:173], v[250:253], v[2:5]
	s_nop 0
	s_barrier
	v_add_u32_e32 v154, s23, v148
	v_add_u32_e32 v170, s22, v148
	ds_read_b128 v[136:139], v154
	ds_read_b128 v[140:143], v154 offset:1024
	ds_read_b128 v[150:153], v154 offset:2048
	ds_read_b128 v[154:157], v154 offset:3072
	ds_read_b128 v[158:161], v170
	ds_read_b128 v[162:165], v170 offset:1024
	ds_read_b128 v[166:169], v170 offset:2048
	ds_read_b128 v[170:173], v170 offset:3072
	s_mov_b32 m0, s47
	v_lshl_add_u64 v[230:231], s[42:43], 0, v[0:1]
	ds_read_b128 v[174:177], v149 offset:32768
	ds_read_b128 v[178:181], v149 offset:33792
	ds_read_b128 v[182:185], v149 offset:34816
	ds_read_b128 v[220:223], v149 offset:35840
	ds_read_b128 v[224:227], v149 offset:36864
	ds_read_b128 v[242:245], v149 offset:37888
	ds_read_b128 v[246:249], v149 offset:38912
	ds_read_b128 v[250:253], v149 offset:39936
	global_load_lds_dwordx4 v[230:231], off
	v_lshl_add_u64 v[230:231], s[42:43], 0, v[132:133]
	s_mov_b32 m0, s55
	s_nop 0
	global_load_lds_dwordx4 v[230:231], off
	s_waitcnt vmcnt(8)
	s_waitcnt lgkmcnt(0)
	s_barrier
	s_nop 0
	s_waitcnt lgkmcnt(0)
	v_mfma_f32_16x16x32_bf16 v[126:129], v[136:139], v[174:177], v[126:129]
	v_mfma_f32_16x16x32_bf16 v[122:125], v[150:153], v[174:177], v[122:125]
	v_mfma_f32_16x16x32_bf16 v[110:113], v[136:139], v[182:185], v[110:113]
	v_mfma_f32_16x16x32_bf16 v[106:109], v[150:153], v[182:185], v[106:109]
	v_mfma_f32_16x16x32_bf16 v[94:97], v[136:139], v[224:227], v[94:97]
	v_mfma_f32_16x16x32_bf16 v[90:93], v[150:153], v[224:227], v[90:93]
	v_mfma_f32_16x16x32_bf16 v[78:81], v[136:139], v[246:249], v[78:81]
	v_mfma_f32_16x16x32_bf16 v[74:77], v[150:153], v[246:249], v[74:77]
	v_mfma_f32_16x16x32_bf16 v[126:129], v[140:143], v[178:181], v[126:129]
	v_mfma_f32_16x16x32_bf16 v[122:125], v[154:157], v[178:181], v[122:125]
	v_mfma_f32_16x16x32_bf16 v[110:113], v[140:143], v[220:223], v[110:113]
	v_mfma_f32_16x16x32_bf16 v[106:109], v[154:157], v[220:223], v[106:109]
	v_mfma_f32_16x16x32_bf16 v[94:97], v[140:143], v[242:245], v[94:97]
	v_mfma_f32_16x16x32_bf16 v[90:93], v[154:157], v[242:245], v[90:93]
	v_mfma_f32_16x16x32_bf16 v[78:81], v[140:143], v[250:253], v[78:81]
	v_mfma_f32_16x16x32_bf16 v[74:77], v[154:157], v[250:253], v[74:77]
	s_nop 0
	s_nop 0
	v_mfma_f32_16x16x32_bf16 v[118:121], v[158:161], v[174:177], v[118:121]
	v_mfma_f32_16x16x32_bf16 v[114:117], v[166:169], v[174:177], v[114:117]
	v_mfma_f32_16x16x32_bf16 v[102:105], v[158:161], v[182:185], v[102:105]
	v_mfma_f32_16x16x32_bf16 v[98:101], v[166:169], v[182:185], v[98:101]
	v_mfma_f32_16x16x32_bf16 v[86:89], v[158:161], v[224:227], v[86:89]
	v_mfma_f32_16x16x32_bf16 v[82:85], v[166:169], v[224:227], v[82:85]
	v_mfma_f32_16x16x32_bf16 v[70:73], v[158:161], v[246:249], v[70:73]
	v_mfma_f32_16x16x32_bf16 v[66:69], v[166:169], v[246:249], v[66:69]
	v_mfma_f32_16x16x32_bf16 v[118:121], v[162:165], v[178:181], v[118:121]
	v_mfma_f32_16x16x32_bf16 v[114:117], v[170:173], v[178:181], v[114:117]
	v_mfma_f32_16x16x32_bf16 v[102:105], v[162:165], v[220:223], v[102:105]
	v_mfma_f32_16x16x32_bf16 v[98:101], v[170:173], v[220:223], v[98:101]
	v_mfma_f32_16x16x32_bf16 v[86:89], v[162:165], v[242:245], v[86:89]
	v_mfma_f32_16x16x32_bf16 v[82:85], v[170:173], v[242:245], v[82:85]
	v_mfma_f32_16x16x32_bf16 v[70:73], v[162:165], v[250:253], v[70:73]
	v_mfma_f32_16x16x32_bf16 v[66:69], v[170:173], v[250:253], v[66:69]
	s_nop 0
	s_barrier
; #define PG8_STAGE(bufoff, gbase, voff) do { _Pragma("unroll") for (int _i = 0; _i < 2; ++_i) \
;         __builtin_amdgcn_global_load_lds((const unsigned*)((const char*)(gbase) + (voff)[_i]), (PG8_LAS unsigned*)(lds + (bufoff) + ldsw + _i * 8192), 16, 0, 0); } while (0)
; #define PG8_LDA(dst, b, h) do { _Pragma("unroll") for (int m = 0; m < 4; ++m) _Pragma("unroll") for (int k = 0; k < 2; ++k) dst[m][k] = *(const PG8_LAS bf16x8*)(lds + PG8_SA(b, h) + aoff + m * 2048 + k * 1024); } while (0)
; #define PG8_MMA(ai, bj, At, Bt) do { __builtin_amdgcn_s_setprio(1); _Pragma("unroll") for (int m = 0; m < 4; ++m) _Pragma("unroll") for (int n = 0; n < 2; ++n) _Pragma("unroll") for (int k = 0; k < 2; ++k) \
;         acc[ai][bj][m][n] = __builtin_amdgcn_mfma_f32_16x16x32_bf16(Bt[n][k], At[m][k], acc[ai][bj][m][n], 0, 0, 0); __builtin_amdgcn_s_setprio(0); } while (0)
; #define PG8_WAIT_V(n) asm volatile("s_waitcnt vmcnt(" #n ")" ::: "memory")
; #define PG8_WAIT_L(n) asm volatile("s_waitcnt lgkmcnt(" #n ")" ::: "memory")
; #define PG8_BAR __builtin_amdgcn_s_barrier()
; #define PG8_SCHED __builtin_amdgcn_sched_barrier(0)
; template <class Epi, class Sched, bool ALIGN_EPI = false, bool SP2 = false>
; __device__ __forceinline__ void gemm_phase(PG8_LAS unsigned char* lds, const Gemm g, const Sched& S, const Epi& E, int wv) {
;     ...
;         for (int t = 0; t < nt; t += 2) {
;             const bool last = (t == nt - 2);
;     ...
;             PG8_LDA(At, 1, 1); PG8_STAGE(PG8_SB(1, 0), b3, voffB); PG8_STAGE(PG8_SB(1, 1), b3 + hstepB, voffB); PG8_STAGE(PG8_SA(1, 0), a3, voffA);
;             PG8_WAIT_V(8); PG8_WAIT_L(0); PG8_BAR; PG8_MMA(1, 0, At, B0); PG8_MMA(1, 1, At, B1); PG8_BAR; PG8_SCHED;
	s_mov_b32 m0, vcc_hi
	v_lshl_add_u64 v[144:145], v[144:145], 0, s[62:63]
	ds_read_b128 v[174:177], v149 offset:49152
	ds_read_b128 v[178:181], v149 offset:50176
	ds_read_b128 v[182:185], v149 offset:51200
	ds_read_b128 v[220:223], v149 offset:52224
	ds_read_b128 v[224:227], v149 offset:53248
	ds_read_b128 v[242:245], v149 offset:54272
	ds_read_b128 v[246:249], v149 offset:55296
	ds_read_b128 v[250:253], v149 offset:56320
	global_load_lds_dwordx4 v[144:145], off
	v_lshl_add_u64 v[144:145], v[186:187], 0, s[62:63]
	s_mov_b32 m0, vcc_lo
	s_nop 0
	global_load_lds_dwordx4 v[144:145], off
	v_lshl_add_u64 v[144:145], s[2:3], 0, v[130:131]
	s_mov_b32 m0, s88
	s_nop 0
	global_load_lds_dwordx4 v[144:145], off
	v_lshl_add_u64 v[144:145], s[2:3], 0, v[134:135]
	s_mov_b32 m0, s60
	s_nop 0
	global_load_lds_dwordx4 v[144:145], off
	v_lshl_add_u64 v[144:145], v[196:197], 0, s[62:63]
	s_mov_b32 m0, s45
	s_nop 0
	global_load_lds_dwordx4 v[144:145], off
	v_lshl_add_u64 v[144:145], v[228:229], 0, s[62:63]
	s_mov_b32 m0, s26
	s_nop 0
	global_load_lds_dwordx4 v[144:145], off
	s_waitcnt vmcnt(8)
	s_waitcnt lgkmcnt(0)
	s_barrier
	s_nop 0
	s_waitcnt lgkmcnt(0)
	v_mfma_f32_16x16x32_bf16 v[62:65], v[136:139], v[174:177], v[62:65]
	v_mfma_f32_16x16x32_bf16 v[58:61], v[150:153], v[174:177], v[58:61]
	v_mfma_f32_16x16x32_bf16 v[46:49], v[136:139], v[182:185], v[46:49]
	v_mfma_f32_16x16x32_bf16 v[42:45], v[150:153], v[182:185], v[42:45]
	v_mfma_f32_16x16x32_bf16 v[30:33], v[136:139], v[224:227], v[30:33]
	v_mfma_f32_16x16x32_bf16 v[26:29], v[150:153], v[224:227], v[26:29]
	v_mfma_f32_16x16x32_bf16 v[14:17], v[136:139], v[246:249], v[14:17]
	v_mfma_f32_16x16x32_bf16 v[10:13], v[150:153], v[246:249], v[10:13]
	v_mfma_f32_16x16x32_bf16 v[62:65], v[140:143], v[178:181], v[62:65]
	v_mfma_f32_16x16x32_bf16 v[58:61], v[154:157], v[178:181], v[58:61]
	v_mfma_f32_16x16x32_bf16 v[46:49], v[140:143], v[220:223], v[46:49]
	v_mfma_f32_16x16x32_bf16 v[42:45], v[154:157], v[220:223], v[42:45]
	v_mfma_f32_16x16x32_bf16 v[30:33], v[140:143], v[242:245], v[30:33]
	v_mfma_f32_16x16x32_bf16 v[26:29], v[154:157], v[242:245], v[26:29]
	v_mfma_f32_16x16x32_bf16 v[14:17], v[140:143], v[250:253], v[14:17]
	v_mfma_f32_16x16x32_bf16 v[10:13], v[154:157], v[250:253], v[10:13]
	s_nop 0
	s_nop 0
	v_mfma_f32_16x16x32_bf16 v[54:57], v[158:161], v[174:177], v[54:57]
	v_mfma_f32_16x16x32_bf16 v[50:53], v[166:169], v[174:177], v[50:53]
	v_mfma_f32_16x16x32_bf16 v[38:41], v[158:161], v[182:185], v[38:41]
	v_mfma_f32_16x16x32_bf16 v[34:37], v[166:169], v[182:185], v[34:37]
	v_mfma_f32_16x16x32_bf16 v[22:25], v[158:161], v[224:227], v[22:25]
	v_mfma_f32_16x16x32_bf16 v[18:21], v[166:169], v[224:227], v[18:21]
	v_mfma_f32_16x16x32_bf16 v[6:9], v[158:161], v[246:249], v[6:9]
	v_mfma_f32_16x16x32_bf16 v[2:5], v[166:169], v[246:249], v[2:5]
	v_mfma_f32_16x16x32_bf16 v[54:57], v[162:165], v[178:181], v[54:57]
	v_mfma_f32_16x16x32_bf16 v[50:53], v[170:173], v[178:181], v[50:53]
	v_mfma_f32_16x16x32_bf16 v[38:41], v[162:165], v[220:223], v[38:41]
	v_mfma_f32_16x16x32_bf16 v[34:37], v[170:173], v[220:223], v[34:37]
	v_mfma_f32_16x16x32_bf16 v[22:25], v[162:165], v[242:245], v[22:25]
	v_mfma_f32_16x16x32_bf16 v[18:21], v[170:173], v[242:245], v[18:21]
	v_mfma_f32_16x16x32_bf16 v[6:9], v[162:165], v[250:253], v[6:9]
	v_mfma_f32_16x16x32_bf16 v[2:5], v[170:173], v[250:253], v[2:5]
	s_nop 0
	s_barrier
	s_andn2_b64 vcc, exec, s[18:19]
	s_mov_b64 s[2:3], -1
	s_mov_b64 s[18:19], 0
	s_mov_b64 s[42:43], 0x100
	s_cbranch_vccz .LBB0_1271
	v_readlane_b32 s2, v254, 61
	v_readlane_b32 s3, v254, 62
	s_and_b64 vcc, exec, s[2:3]
	s_cbranch_vccz .LBB0_1274
	s_barrier

; #define PG8_STAGE(bufoff, gbase, voff) do { _Pragma("unroll") for (int _i = 0; _i < 2; ++_i) \
;         __builtin_amdgcn_global_load_lds((const unsigned*)((const char*)(gbase) + (voff)[_i]), (PG8_LAS unsigned*)(lds + (bufoff) + ldsw + _i * 8192), 16, 0, 0); } while (0)
; #define PG8_LDA(dst, b, h) do { _Pragma("unroll") for (int m = 0; m < 4; ++m) _Pragma("unroll") for (int k = 0; k < 2; ++k) dst[m][k] = *(const PG8_LAS bf16x8*)(lds + PG8_SA(b, h) + aoff + m * 2048 + k * 1024); } while (0)
; #define PG8_LDB(dst, b, h) do { _Pragma("unroll") for (int n = 0; n < 2; ++n) _Pragma("unroll") for (int k = 0; k < 2; ++k) dst[n][k] = *(const PG8_LAS bf16x8*)(lds + PG8_SB(b, h) + boff + n * 2048 + k * 1024); } while (0)
; #define PG8_MMA(ai, bj, At, Bt) do { __builtin_amdgcn_s_setprio(1); _Pragma("unroll") for (int m = 0; m < 4; ++m) _Pragma("unroll") for (int n = 0; n < 2; ++n) _Pragma("unroll") for (int k = 0; k < 2; ++k) \
;         acc[ai][bj][m][n] = __builtin_amdgcn_mfma_f32_16x16x32_bf16(Bt[n][k], At[m][k], acc[ai][bj][m][n], 0, 0, 0); __builtin_amdgcn_s_setprio(0); } while (0)
; #define PG8_WAIT_V(n) asm volatile("s_waitcnt vmcnt(" #n ")" ::: "memory")
; #define PG8_WAIT_L(n) asm volatile("s_waitcnt lgkmcnt(" #n ")" ::: "memory")
; #define PG8_BAR __builtin_amdgcn_s_barrier()
; #define PG8_SCHED __builtin_amdgcn_sched_barrier(0)
; template <class Epi, class Sched, bool ALIGN_EPI = false, bool SP2 = false>
; __device__ __forceinline__ void gemm_phase(PG8_LAS unsigned char* lds, const Gemm g, const Sched& S, const Epi& E, int wv) {
;     ...
;             const bool last = (t == nt - 2);
;             const char* a1 = cA + (size_t)(t + 1) * kstep;
;             const char* a2 = last ? nA : cA + (size_t)(t + 2) * kstep; const char* b2 = last ? nB : cB + (size_t)(t + 2) * kstep;
;             const char* a3 = a2 + kstep; const char* b3 = b2 + kstep;
;             if (last && has_next) S.a_ready(nxt);
;             if constexpr (SP2) {
;             PG8_LDB(B0, 0, 0); PG8_LDB(B1, 0, 1); PG8_SCHED; PG8_LDA(At, 0, 0); PG8_STAGE(PG8_SA(1, 1), a1 + hstepA, voffA);
;             PG8_WAIT_V(8); PG8_WAIT_L(0); PG8_BAR; PG8_MMA(0, 0, At, B0); PG8_MMA(0, 1, At, B1); PG8_BAR; PG8_SCHED;
;             PG8_LDA(At, 0, 1); PG8_STAGE(PG8_SB(0, 0), b2, voffB); PG8_STAGE(PG8_SB(0, 1), b2 + hstepB, voffB); PG8_STAGE(PG8_SA(0, 0), a2, voffA);
.LBB0_1743:
	s_add_u32 s2, s20, 0xfffc0080
	s_addc_u32 s3, s21, -1
	s_add_i32 s60, 0, 0x10000
	s_cmp_eq_u32 s97, 12
	s_cselect_b32 s35, s15, s3
	s_cselect_b32 s34, s19, s2
	s_cselect_b32 s3, s45, s95
	s_cselect_b32 s2, s47, s94
	s_add_i32 s61, 0, 0x14000
	v_add_u32_e32 v152, s60, v160
	v_add_u32_e32 v156, s61, v160
	ds_read_b128 v[130:133], v152
	ds_read_b128 v[134:137], v152 offset:1024
	ds_read_b128 v[148:151], v152 offset:2048
	ds_read_b128 v[152:155], v152 offset:3072
	ds_read_b128 v[162:165], v156
	ds_read_b128 v[166:169], v156 offset:1024
	ds_read_b128 v[170:173], v156 offset:2048
	ds_read_b128 v[174:177], v156 offset:3072
	v_lshl_add_u64 v[156:157], s[20:21], 0, v[144:145]
	s_add_i32 m0, s43, 0xc000
	ds_read_b128 v[178:181], v161
	ds_read_b128 v[182:185], v161 offset:1024
	ds_read_b128 v[220:223], v161 offset:2048
	ds_read_b128 v[224:227], v161 offset:3072
	ds_read_b128 v[242:245], v161 offset:4096
	ds_read_b128 v[246:249], v161 offset:5120
	ds_read_b128 v[250:253], v161 offset:6144
	ds_read_b128 v[228:231], v161 offset:7168
	global_load_lds_dwordx4 v[156:157], off
	v_lshl_add_u64 v[156:157], s[20:21], 0, v[146:147]
	s_add_i32 m0, s43, 0xe000
	s_nop 0
	global_load_lds_dwordx4 v[156:157], off
	s_waitcnt vmcnt(8)
	s_waitcnt lgkmcnt(0)
	s_barrier
	s_nop 0
	s_waitcnt lgkmcnt(0)
	v_mfma_f32_16x16x32_bf16 v[126:129], v[130:133], v[178:181], v[126:129]
	v_mfma_f32_16x16x32_bf16 v[122:125], v[148:151], v[178:181], v[122:125]
	v_mfma_f32_16x16x32_bf16 v[110:113], v[130:133], v[220:223], v[110:113]
	v_mfma_f32_16x16x32_bf16 v[106:109], v[148:151], v[220:223], v[106:109]
	v_mfma_f32_16x16x32_bf16 v[94:97], v[130:133], v[242:245], v[94:97]
	v_mfma_f32_16x16x32_bf16 v[90:93], v[148:151], v[242:245], v[90:93]
	v_mfma_f32_16x16x32_bf16 v[78:81], v[130:133], v[250:253], v[78:81]
	v_mfma_f32_16x16x32_bf16 v[74:77], v[148:151], v[250:253], v[74:77]
	v_mfma_f32_16x16x32_bf16 v[126:129], v[134:137], v[182:185], v[126:129]
	v_mfma_f32_16x16x32_bf16 v[122:125], v[152:155], v[182:185], v[122:125]
	v_mfma_f32_16x16x32_bf16 v[110:113], v[134:137], v[224:227], v[110:113]
	v_mfma_f32_16x16x32_bf16 v[106:109], v[152:155], v[224:227], v[106:109]
	v_mfma_f32_16x16x32_bf16 v[94:97], v[134:137], v[246:249], v[94:97]
	v_mfma_f32_16x16x32_bf16 v[90:93], v[152:155], v[246:249], v[90:93]
	v_mfma_f32_16x16x32_bf16 v[78:81], v[134:137], v[228:231], v[78:81]
	v_mfma_f32_16x16x32_bf16 v[74:77], v[152:155], v[228:231], v[74:77]
	s_nop 0
	s_nop 0
	v_mfma_f32_16x16x32_bf16 v[118:121], v[162:165], v[178:181], v[118:121]
	v_mfma_f32_16x16x32_bf16 v[114:117], v[170:173], v[178:181], v[114:117]
	v_mfma_f32_16x16x32_bf16 v[102:105], v[162:165], v[220:223], v[102:105]
	v_mfma_f32_16x16x32_bf16 v[98:101], v[170:173], v[220:223], v[98:101]
	v_mfma_f32_16x16x32_bf16 v[86:89], v[162:165], v[242:245], v[86:89]
	v_mfma_f32_16x16x32_bf16 v[82:85], v[170:173], v[242:245], v[82:85]
	v_mfma_f32_16x16x32_bf16 v[70:73], v[162:165], v[250:253], v[70:73]
	v_mfma_f32_16x16x32_bf16 v[66:69], v[170:173], v[250:253], v[66:69]
	v_mfma_f32_16x16x32_bf16 v[118:121], v[166:169], v[182:185], v[118:121]
	v_mfma_f32_16x16x32_bf16 v[114:117], v[174:177], v[182:185], v[114:117]
	v_mfma_f32_16x16x32_bf16 v[102:105], v[166:169], v[224:227], v[102:105]
	v_mfma_f32_16x16x32_bf16 v[98:101], v[174:177], v[224:227], v[98:101]
	v_mfma_f32_16x16x32_bf16 v[86:89], v[166:169], v[246:249], v[86:89]
	v_mfma_f32_16x16x32_bf16 v[82:85], v[174:177], v[246:249], v[82:85]
	v_mfma_f32_16x16x32_bf16 v[70:73], v[166:169], v[228:231], v[70:73]
	v_mfma_f32_16x16x32_bf16 v[66:69], v[174:177], v[228:231], v[66:69]
	s_nop 0
	s_barrier
	s_add_i32 s60, s60, s42
	v_lshl_add_u64 v[156:157], s[2:3], 0, v[0:1]
	s_mov_b32 m0, s60
	ds_read_b128 v[178:181], v161 offset:16384
	ds_read_b128 v[182:185], v161 offset:17408
	ds_read_b128 v[220:223], v161 offset:18432
	ds_read_b128 v[224:227], v161 offset:19456
	ds_read_b128 v[228:231], v161 offset:20480
	ds_read_b128 v[242:245], v161 offset:21504
	ds_read_b128 v[246:249], v161 offset:22528
	ds_read_b128 v[250:253], v161 offset:23552
	global_load_lds_dwordx4 v[156:157], off
	s_add_i32 m0, s60, 0x2000
	s_add_u32 vcc_lo, s2, 0x40000
	v_lshl_add_u64 v[186:187], s[2:3], 0, v[142:143]
	s_addc_u32 vcc_hi, s3, 0
	s_add_i32 s60, s61, s42
	global_load_lds_dwordx4 v[186:187], off
	v_lshl_add_u64 v[196:197], vcc, 0, v[0:1]
	s_mov_b32 m0, s60
	v_lshl_add_u64 v[232:233], s[34:35], 0, v[140:141]
	global_load_lds_dwordx4 v[196:197], off
	v_lshl_add_u64 v[196:197], vcc, 0, v[142:143]
	s_add_i32 m0, s60, 0x2000
	s_nop 0
	global_load_lds_dwordx4 v[196:197], off
	v_lshl_add_u64 v[196:197], s[34:35], 0, v[138:139]
	s_mov_b32 m0, s43
	s_nop 0
	global_load_lds_dwordx4 v[196:197], off
	s_mov_b32 m0, s52
	s_nop 0
	global_load_lds_dwordx4 v[232:233], off
	s_waitcnt vmcnt(8)
	s_waitcnt lgkmcnt(0)
	s_barrier
; #define PG8_STAGE(bufoff, gbase, voff) do { _Pragma("unroll") for (int _i = 0; _i < 2; ++_i) \
;         __builtin_amdgcn_global_load_lds((const unsigned*)((const char*)(gbase) + (voff)[_i]), (PG8_LAS unsigned*)(lds + (bufoff) + ldsw + _i * 8192), 16, 0, 0); } while (0)
; #define PG8_LDA(dst, b, h) do { _Pragma("unroll") for (int m = 0; m < 4; ++m) _Pragma("unroll") for (int k = 0; k < 2; ++k) dst[m][k] = *(const PG8_LAS bf16x8*)(lds + PG8_SA(b, h) + aoff + m * 2048 + k * 1024); } while (0)
; #define PG8_LDB(dst, b, h) do { _Pragma("unroll") for (int n = 0; n < 2; ++n) _Pragma("unroll") for (int k = 0; k < 2; ++k) dst[n][k] = *(const PG8_LAS bf16x8*)(lds + PG8_SB(b, h) + boff + n * 2048 + k * 1024); } while (0)
; #define PG8_MMA(ai, bj, At, Bt) do { __builtin_amdgcn_s_setprio(1); _Pragma("unroll") for (int m = 0; m < 4; ++m) _Pragma("unroll") for (int n = 0; n < 2; ++n) _Pragma("unroll") for (int k = 0; k < 2; ++k) \
;         acc[ai][bj][m][n] = __builtin_amdgcn_mfma_f32_16x16x32_bf16(Bt[n][k], At[m][k], acc[ai][bj][m][n], 0, 0, 0); __builtin_amdgcn_s_setprio(0); } while (0)
; #define PG8_WAIT_V(n) asm volatile("s_waitcnt vmcnt(" #n ")" ::: "memory")
; #define PG8_WAIT_L(n) asm volatile("s_waitcnt lgkmcnt(" #n ")" ::: "memory")
; #define PG8_BAR __builtin_amdgcn_s_barrier()
; #define PG8_SCHED __builtin_amdgcn_sched_barrier(0)
; template <class Epi, class Sched, bool ALIGN_EPI = false, bool SP2 = false>
; __device__ __forceinline__ void gemm_phase(PG8_LAS unsigned char* lds, const Gemm g, const Sched& S, const Epi& E, int wv) {
;     ...
;             PG8_WAIT_V(8); PG8_WAIT_L(0); PG8_BAR; PG8_MMA(1, 0, At, B0); PG8_MMA(1, 1, At, B1); PG8_BAR; PG8_SCHED;
;             PG8_LDB(B0, 1, 0); PG8_LDB(B1, 1, 1); PG8_SCHED; PG8_LDA(At, 1, 0); PG8_STAGE(PG8_SA(0, 1), a2 + hstepA, voffA);
;             PG8_WAIT_V(8); PG8_WAIT_L(0); PG8_BAR; PG8_MMA(0, 0, At, B0); PG8_MMA(0, 1, At, B1); PG8_BAR; PG8_SCHED;
	s_nop 0
	s_waitcnt lgkmcnt(0)
	v_mfma_f32_16x16x32_bf16 v[62:65], v[130:133], v[178:181], v[62:65]
	v_mfma_f32_16x16x32_bf16 v[58:61], v[148:151], v[178:181], v[58:61]
	v_mfma_f32_16x16x32_bf16 v[46:49], v[130:133], v[220:223], v[46:49]
	v_mfma_f32_16x16x32_bf16 v[42:45], v[148:151], v[220:223], v[42:45]
	v_mfma_f32_16x16x32_bf16 v[30:33], v[130:133], v[228:231], v[30:33]
	v_mfma_f32_16x16x32_bf16 v[26:29], v[148:151], v[228:231], v[26:29]
	v_mfma_f32_16x16x32_bf16 v[14:17], v[130:133], v[246:249], v[14:17]
	v_mfma_f32_16x16x32_bf16 v[10:13], v[148:151], v[246:249], v[10:13]
	v_mfma_f32_16x16x32_bf16 v[62:65], v[134:137], v[182:185], v[62:65]
	v_mfma_f32_16x16x32_bf16 v[58:61], v[152:155], v[182:185], v[58:61]
	v_mfma_f32_16x16x32_bf16 v[46:49], v[134:137], v[224:227], v[46:49]
	v_mfma_f32_16x16x32_bf16 v[42:45], v[152:155], v[224:227], v[42:45]
	v_mfma_f32_16x16x32_bf16 v[30:33], v[134:137], v[242:245], v[30:33]
	v_mfma_f32_16x16x32_bf16 v[26:29], v[152:155], v[242:245], v[26:29]
	v_mfma_f32_16x16x32_bf16 v[14:17], v[134:137], v[250:253], v[14:17]
	v_mfma_f32_16x16x32_bf16 v[10:13], v[152:155], v[250:253], v[10:13]
	s_nop 0
	s_nop 0
	v_mfma_f32_16x16x32_bf16 v[54:57], v[162:165], v[178:181], v[54:57]
	v_mfma_f32_16x16x32_bf16 v[50:53], v[170:173], v[178:181], v[50:53]
	v_mfma_f32_16x16x32_bf16 v[38:41], v[162:165], v[220:223], v[38:41]
	v_mfma_f32_16x16x32_bf16 v[34:37], v[170:173], v[220:223], v[34:37]
	v_mfma_f32_16x16x32_bf16 v[22:25], v[162:165], v[228:231], v[22:25]
	v_mfma_f32_16x16x32_bf16 v[18:21], v[170:173], v[228:231], v[18:21]
	v_mfma_f32_16x16x32_bf16 v[6:9], v[162:165], v[246:249], v[6:9]
	v_mfma_f32_16x16x32_bf16 v[2:5], v[170:173], v[246:249], v[2:5]
	v_mfma_f32_16x16x32_bf16 v[54:57], v[166:169], v[182:185], v[54:57]
	v_mfma_f32_16x16x32_bf16 v[50:53], v[174:177], v[182:185], v[50:53]
	v_mfma_f32_16x16x32_bf16 v[38:41], v[166:169], v[224:227], v[38:41]
	v_mfma_f32_16x16x32_bf16 v[34:37], v[174:177], v[224:227], v[34:37]
	v_mfma_f32_16x16x32_bf16 v[22:25], v[166:169], v[242:245], v[22:25]
	v_mfma_f32_16x16x32_bf16 v[18:21], v[174:177], v[242:245], v[18:21]
	v_mfma_f32_16x16x32_bf16 v[6:9], v[166:169], v[250:253], v[6:9]
	v_mfma_f32_16x16x32_bf16 v[2:5], v[174:177], v[250:253], v[2:5]
	s_nop 0
	s_barrier
	s_add_i32 s60, 0, 0x18000
	s_add_i32 s61, 0, 0x1c000
	v_add_u32_e32 v152, s60, v160
	v_add_u32_e32 v174, s61, v160
	ds_read_b128 v[130:133], v152
	ds_read_b128 v[134:137], v152 offset:1024
	ds_read_b128 v[148:151], v152 offset:2048
	ds_read_b128 v[152:155], v152 offset:3072
	ds_read_b128 v[162:165], v174
	ds_read_b128 v[166:169], v174 offset:1024
	ds_read_b128 v[170:173], v174 offset:2048
	ds_read_b128 v[174:177], v174 offset:3072
	s_add_u32 s34, s34, 0x40000
	s_addc_u32 s35, s35, 0
	s_mov_b32 m0, s53
	v_lshl_add_u64 v[234:235], s[34:35], 0, v[138:139]
	ds_read_b128 v[178:181], v161 offset:32768
	ds_read_b128 v[182:185], v161 offset:33792
	ds_read_b128 v[220:223], v161 offset:34816
	ds_read_b128 v[224:227], v161 offset:35840
	ds_read_b128 v[228:231], v161 offset:36864
	ds_read_b128 v[242:245], v161 offset:37888
	ds_read_b128 v[246:249], v161 offset:38912
	ds_read_b128 v[250:253], v161 offset:39936
	global_load_lds_dwordx4 v[234:235], off
	v_lshl_add_u64 v[234:235], s[34:35], 0, v[140:141]
	s_mov_b32 m0, s55
	s_nop 0
	global_load_lds_dwordx4 v[234:235], off
	s_waitcnt vmcnt(8)
	s_waitcnt lgkmcnt(0)
	s_barrier
	s_nop 0
	s_waitcnt lgkmcnt(0)
	v_mfma_f32_16x16x32_bf16 v[126:129], v[130:133], v[178:181], v[126:129]
	v_mfma_f32_16x16x32_bf16 v[122:125], v[148:151], v[178:181], v[122:125]
	v_mfma_f32_16x16x32_bf16 v[110:113], v[130:133], v[220:223], v[110:113]
	v_mfma_f32_16x16x32_bf16 v[106:109], v[148:151], v[220:223], v[106:109]
	v_mfma_f32_16x16x32_bf16 v[94:97], v[130:133], v[228:231], v[94:97]
	v_mfma_f32_16x16x32_bf16 v[90:93], v[148:151], v[228:231], v[90:93]
	v_mfma_f32_16x16x32_bf16 v[78:81], v[130:133], v[246:249], v[78:81]
	v_mfma_f32_16x16x32_bf16 v[74:77], v[148:151], v[246:249], v[74:77]
	v_mfma_f32_16x16x32_bf16 v[126:129], v[134:137], v[182:185], v[126:129]
	v_mfma_f32_16x16x32_bf16 v[122:125], v[152:155], v[182:185], v[122:125]
	v_mfma_f32_16x16x32_bf16 v[110:113], v[134:137], v[224:227], v[110:113]
	v_mfma_f32_16x16x32_bf16 v[106:109], v[152:155], v[224:227], v[106:109]
	v_mfma_f32_16x16x32_bf16 v[94:97], v[134:137], v[242:245], v[94:97]
	v_mfma_f32_16x16x32_bf16 v[90:93], v[152:155], v[242:245], v[90:93]
	v_mfma_f32_16x16x32_bf16 v[78:81], v[134:137], v[250:253], v[78:81]
	v_mfma_f32_16x16x32_bf16 v[74:77], v[152:155], v[250:253], v[74:77]
	s_nop 0
	s_nop 0
	v_mfma_f32_16x16x32_bf16 v[118:121], v[162:165], v[178:181], v[118:121]
	v_mfma_f32_16x16x32_bf16 v[114:117], v[170:173], v[178:181], v[114:117]
	v_mfma_f32_16x16x32_bf16 v[102:105], v[162:165], v[220:223], v[102:105]
	v_mfma_f32_16x16x32_bf16 v[98:101], v[170:173], v[220:223], v[98:101]
	v_mfma_f32_16x16x32_bf16 v[86:89], v[162:165], v[228:231], v[86:89]
	v_mfma_f32_16x16x32_bf16 v[82:85], v[170:173], v[228:231], v[82:85]
	v_mfma_f32_16x16x32_bf16 v[70:73], v[162:165], v[246:249], v[70:73]
	v_mfma_f32_16x16x32_bf16 v[66:69], v[170:173], v[246:249], v[66:69]
	v_mfma_f32_16x16x32_bf16 v[118:121], v[166:169], v[182:185], v[118:121]
	v_mfma_f32_16x16x32_bf16 v[114:117], v[174:177], v[182:185], v[114:117]
	v_mfma_f32_16x16x32_bf16 v[102:105], v[166:169], v[224:227], v[102:105]
	v_mfma_f32_16x16x32_bf16 v[98:101], v[174:177], v[224:227], v[98:101]
	v_mfma_f32_16x16x32_bf16 v[86:89], v[166:169], v[242:245], v[86:89]
	v_mfma_f32_16x16x32_bf16 v[82:85], v[174:177], v[242:245], v[82:85]
	v_mfma_f32_16x16x32_bf16 v[70:73], v[166:169], v[250:253], v[70:73]
	v_mfma_f32_16x16x32_bf16 v[66:69], v[174:177], v[250:253], v[66:69]
	s_nop 0
	s_barrier
; #define PG8_STAGE(bufoff, gbase, voff) do { _Pragma("unroll") for (int _i = 0; _i < 2; ++_i) \
;         __builtin_amdgcn_global_load_lds((const unsigned*)((const char*)(gbase) + (voff)[_i]), (PG8_LAS unsigned*)(lds + (bufoff) + ldsw + _i * 8192), 16, 0, 0); } while (0)
; #define PG8_LDA(dst, b, h) do { _Pragma("unroll") for (int m = 0; m < 4; ++m) _Pragma("unroll") for (int k = 0; k < 2; ++k) dst[m][k] = *(const PG8_LAS bf16x8*)(lds + PG8_SA(b, h) + aoff + m * 2048 + k * 1024); } while (0)
; #define PG8_MMA(ai, bj, At, Bt) do { __builtin_amdgcn_s_setprio(1); _Pragma("unroll") for (int m = 0; m < 4; ++m) _Pragma("unroll") for (int n = 0; n < 2; ++n) _Pragma("unroll") for (int k = 0; k < 2; ++k) \
;         acc[ai][bj][m][n] = __builtin_amdgcn_mfma_f32_16x16x32_bf16(Bt[n][k], At[m][k], acc[ai][bj][m][n], 0, 0, 0); __builtin_amdgcn_s_setprio(0); } while (0)
; #define PG8_WAIT_V(n) asm volatile("s_waitcnt vmcnt(" #n ")" ::: "memory")
; #define PG8_WAIT_L(n) asm volatile("s_waitcnt lgkmcnt(" #n ")" ::: "memory")
; #define PG8_BAR __builtin_amdgcn_s_barrier()
; #define PG8_SCHED __builtin_amdgcn_sched_barrier(0)
; template <class Epi, class Sched, bool ALIGN_EPI = false, bool SP2 = false>
; __device__ __forceinline__ void gemm_phase(PG8_LAS unsigned char* lds, const Gemm g, const Sched& S, const Epi& E, int wv) {
;     ...
;         for (int t = 0; t < nt; t += 2) {
;             const bool last = (t == nt - 2);
;     ...
;             PG8_LDA(At, 1, 1); PG8_STAGE(PG8_SB(1, 0), b3, voffB); PG8_STAGE(PG8_SB(1, 1), b3 + hstepB, voffB); PG8_STAGE(PG8_SA(1, 0), a3, voffA);
;             PG8_WAIT_V(8); PG8_WAIT_L(0); PG8_BAR; PG8_MMA(1, 0, At, B0); PG8_MMA(1, 1, At, B1); PG8_BAR; PG8_SCHED;
	s_add_i32 s34, s60, s42
	v_lshl_add_u64 v[156:157], v[156:157], 0, s[62:63]
	s_mov_b32 m0, s34
	ds_read_b128 v[178:181], v161 offset:49152
	ds_read_b128 v[182:185], v161 offset:50176
	ds_read_b128 v[220:223], v161 offset:51200
	ds_read_b128 v[224:227], v161 offset:52224
	ds_read_b128 v[228:231], v161 offset:53248
	ds_read_b128 v[242:245], v161 offset:54272
	ds_read_b128 v[246:249], v161 offset:55296
	ds_read_b128 v[250:253], v161 offset:56320
	global_load_lds_dwordx4 v[156:157], off
	s_add_i32 m0, s34, 0x2000
	s_add_u32 s2, s2, 0x40080
	v_lshl_add_u64 v[156:157], v[186:187], 0, s[62:63]
	s_addc_u32 s3, s3, 0
	s_add_i32 s34, s61, s42
	global_load_lds_dwordx4 v[156:157], off
	v_lshl_add_u64 v[156:157], s[2:3], 0, v[0:1]
	s_mov_b32 m0, s34
	s_nop 0
	global_load_lds_dwordx4 v[156:157], off
	v_lshl_add_u64 v[156:157], s[2:3], 0, v[142:143]
	s_add_i32 m0, s34, 0x2000
	s_nop 0
	global_load_lds_dwordx4 v[156:157], off
	v_lshl_add_u64 v[156:157], v[196:197], 0, s[62:63]
	s_mov_b32 m0, s83
	s_nop 0
	global_load_lds_dwordx4 v[156:157], off
	v_lshl_add_u64 v[156:157], v[232:233], 0, s[62:63]
	s_mov_b32 m0, s87
	s_nop 0
	global_load_lds_dwordx4 v[156:157], off
	s_waitcnt vmcnt(8)
	s_waitcnt lgkmcnt(0)
	s_barrier
	s_nop 0
	s_waitcnt lgkmcnt(0)
	v_mfma_f32_16x16x32_bf16 v[62:65], v[130:133], v[178:181], v[62:65]
	v_mfma_f32_16x16x32_bf16 v[58:61], v[148:151], v[178:181], v[58:61]
	v_mfma_f32_16x16x32_bf16 v[46:49], v[130:133], v[220:223], v[46:49]
	v_mfma_f32_16x16x32_bf16 v[42:45], v[148:151], v[220:223], v[42:45]
	v_mfma_f32_16x16x32_bf16 v[30:33], v[130:133], v[228:231], v[30:33]
	v_mfma_f32_16x16x32_bf16 v[26:29], v[148:151], v[228:231], v[26:29]
	v_mfma_f32_16x16x32_bf16 v[14:17], v[130:133], v[246:249], v[14:17]
	v_mfma_f32_16x16x32_bf16 v[10:13], v[148:151], v[246:249], v[10:13]
	v_mfma_f32_16x16x32_bf16 v[62:65], v[134:137], v[182:185], v[62:65]
	v_mfma_f32_16x16x32_bf16 v[58:61], v[152:155], v[182:185], v[58:61]
	v_mfma_f32_16x16x32_bf16 v[46:49], v[134:137], v[224:227], v[46:49]
	v_mfma_f32_16x16x32_bf16 v[42:45], v[152:155], v[224:227], v[42:45]
	v_mfma_f32_16x16x32_bf16 v[30:33], v[134:137], v[242:245], v[30:33]
	v_mfma_f32_16x16x32_bf16 v[26:29], v[152:155], v[242:245], v[26:29]
	v_mfma_f32_16x16x32_bf16 v[14:17], v[134:137], v[250:253], v[14:17]
	v_mfma_f32_16x16x32_bf16 v[10:13], v[152:155], v[250:253], v[10:13]
	s_nop 0
	s_nop 0
	v_mfma_f32_16x16x32_bf16 v[54:57], v[162:165], v[178:181], v[54:57]
	v_mfma_f32_16x16x32_bf16 v[50:53], v[170:173], v[178:181], v[50:53]
	v_mfma_f32_16x16x32_bf16 v[38:41], v[162:165], v[220:223], v[38:41]
	v_mfma_f32_16x16x32_bf16 v[34:37], v[170:173], v[220:223], v[34:37]
	v_mfma_f32_16x16x32_bf16 v[22:25], v[162:165], v[228:231], v[22:25]
	v_mfma_f32_16x16x32_bf16 v[18:21], v[170:173], v[228:231], v[18:21]
	v_mfma_f32_16x16x32_bf16 v[6:9], v[162:165], v[246:249], v[6:9]
	v_mfma_f32_16x16x32_bf16 v[2:5], v[170:173], v[246:249], v[2:5]
	v_mfma_f32_16x16x32_bf16 v[54:57], v[166:169], v[182:185], v[54:57]
	v_mfma_f32_16x16x32_bf16 v[50:53], v[174:177], v[182:185], v[50:53]
	v_mfma_f32_16x16x32_bf16 v[38:41], v[166:169], v[224:227], v[38:41]
	v_mfma_f32_16x16x32_bf16 v[34:37], v[174:177], v[224:227], v[34:37]
	v_mfma_f32_16x16x32_bf16 v[22:25], v[166:169], v[242:245], v[22:25]
	v_mfma_f32_16x16x32_bf16 v[18:21], v[174:177], v[242:245], v[18:21]
	v_mfma_f32_16x16x32_bf16 v[6:9], v[166:169], v[250:253], v[6:9]
	v_mfma_f32_16x16x32_bf16 v[2:5], v[174:177], v[250:253], v[2:5]
	s_nop 0
	s_barrier
	s_add_i32 s97, s97, 2
	s_add_u32 s20, s20, 0x100
	s_addc_u32 s21, s21, 0
	s_add_u32 s94, s94, 0x100
	s_addc_u32 s95, s95, 0
	s_cmp_gt_u32 s97, 13
	s_cbranch_scc0 .LBB0_1743
	s_and_b64 vcc, exec, s[36:37]
	s_cbranch_vccz .LBB0_1746
	s_barrier

; #define PG8_STAGE(bufoff, gbase, voff) do { _Pragma("unroll") for (int _i = 0; _i < 2; ++_i) \
;         __builtin_amdgcn_global_load_lds((const unsigned*)((const char*)(gbase) + (voff)[_i]), (PG8_LAS unsigned*)(lds + (bufoff) + ldsw + _i * 8192), 16, 0, 0); } while (0)
; #define PG8_LDA(dst, b, h) do { _Pragma("unroll") for (int m = 0; m < 4; ++m) _Pragma("unroll") for (int k = 0; k < 2; ++k) dst[m][k] = *(const PG8_LAS bf16x8*)(lds + PG8_SA(b, h) + aoff + m * 2048 + k * 1024); } while (0)
; #define PG8_LDB(dst, b, h) do { _Pragma("unroll") for (int n = 0; n < 2; ++n) _Pragma("unroll") for (int k = 0; k < 2; ++k) dst[n][k] = *(const PG8_LAS bf16x8*)(lds + PG8_SB(b, h) + boff + n * 2048 + k * 1024); } while (0)
; #define PG8_MMA(ai, bj, At, Bt) do { __builtin_amdgcn_s_setprio(1); _Pragma("unroll") for (int m = 0; m < 4; ++m) _Pragma("unroll") for (int n = 0; n < 2; ++n) _Pragma("unroll") for (int k = 0; k < 2; ++k) \
;         acc[ai][bj][m][n] = __builtin_amdgcn_mfma_f32_16x16x32_bf16(Bt[n][k], At[m][k], acc[ai][bj][m][n], 0, 0, 0); __builtin_amdgcn_s_setprio(0); } while (0)
; #define PG8_WAIT_V(n) asm volatile("s_waitcnt vmcnt(" #n ")" ::: "memory")
; #define PG8_WAIT_L(n) asm volatile("s_waitcnt lgkmcnt(" #n ")" ::: "memory")
; #define PG8_BAR __builtin_amdgcn_s_barrier()
; #define PG8_SCHED __builtin_amdgcn_sched_barrier(0)
; template <class Epi, class Sched, bool ALIGN_EPI = false, bool SP2 = false>
; __device__ __forceinline__ void gemm_phase(PG8_LAS unsigned char* lds, const Gemm g, const Sched& S, const Epi& E, int wv) {
;     ...
;             const bool last = (t == nt - 2);
;             const char* a1 = cA + (size_t)(t + 1) * kstep;
;             const char* a2 = last ? nA : cA + (size_t)(t + 2) * kstep; const char* b2 = last ? nB : cB + (size_t)(t + 2) * kstep;
;             const char* a3 = a2 + kstep; const char* b3 = b2 + kstep;
;             if (last && has_next) S.a_ready(nxt);
;             if constexpr (SP2) {
;             PG8_LDB(B0, 0, 0); PG8_LDB(B1, 0, 1); PG8_SCHED; PG8_LDA(At, 0, 0); PG8_STAGE(PG8_SA(1, 1), a1 + hstepA, voffA);
;             PG8_WAIT_V(8); PG8_WAIT_L(0); PG8_BAR; PG8_MMA(0, 0, At, B0); PG8_MMA(0, 1, At, B1); PG8_BAR; PG8_SCHED;
;             PG8_LDA(At, 0, 1); PG8_STAGE(PG8_SB(0, 0), b2, voffB); PG8_STAGE(PG8_SB(0, 1), b2 + hstepB, voffB); PG8_STAGE(PG8_SA(0, 0), a2, voffA);
.LBB0_1893:
	s_add_u32 s2, s40, 0xfffc0080
	s_addc_u32 s3, s41, -1
	s_add_i32 s60, 0, 0x10000
	s_cmp_eq_u32 s96, 12
	s_cselect_b32 s43, s39, s3
	s_cselect_b32 s42, s92, s2
	s_cselect_b32 s3, s37, s95
	s_cselect_b32 s2, s93, s94
	s_add_i32 s61, 0, 0x14000
	v_add_u32_e32 v46, s60, v180
	v_add_u32_e32 v62, s61, v180
	ds_read_b128 v[34:37], v46
	ds_read_b128 v[38:41], v46 offset:1024
	ds_read_b128 v[42:45], v46 offset:2048
	ds_read_b128 v[46:49], v46 offset:3072
	ds_read_b128 v[50:53], v62
	ds_read_b128 v[54:57], v62 offset:1024
	ds_read_b128 v[58:61], v62 offset:2048
	ds_read_b128 v[62:65], v62 offset:3072
	v_lshl_add_u64 v[176:177], s[40:41], 0, v[168:169]
	s_add_i32 m0, s35, 0xc000
	ds_read_b128 v[172:175], v181
	ds_read_b128 v[182:185], v181 offset:1024
	ds_read_b128 v[220:223], v181 offset:2048
	ds_read_b128 v[224:227], v181 offset:3072
	ds_read_b128 v[228:231], v181 offset:4096
	ds_read_b128 v[242:245], v181 offset:5120
	ds_read_b128 v[246:249], v181 offset:6144
	ds_read_b128 v[250:253], v181 offset:7168
	global_load_lds_dwordx4 v[176:177], off
	v_lshl_add_u64 v[176:177], s[40:41], 0, v[170:171]
	s_add_i32 m0, s35, 0xe000
	s_nop 0
	global_load_lds_dwordx4 v[176:177], off
	s_waitcnt vmcnt(8)
	s_waitcnt lgkmcnt(0)
	s_barrier
	s_nop 0
	s_waitcnt lgkmcnt(0)
	v_mfma_f32_16x16x32_bf16 v[158:161], v[34:37], v[172:175], v[158:161]
	v_mfma_f32_16x16x32_bf16 v[154:157], v[42:45], v[172:175], v[154:157]
	v_mfma_f32_16x16x32_bf16 v[142:145], v[34:37], v[220:223], v[142:145]
	v_mfma_f32_16x16x32_bf16 v[138:141], v[42:45], v[220:223], v[138:141]
	v_mfma_f32_16x16x32_bf16 v[126:129], v[34:37], v[228:231], v[126:129]
	v_mfma_f32_16x16x32_bf16 v[122:125], v[42:45], v[228:231], v[122:125]
	v_mfma_f32_16x16x32_bf16 v[110:113], v[34:37], v[246:249], v[110:113]
	v_mfma_f32_16x16x32_bf16 v[106:109], v[42:45], v[246:249], v[106:109]
	v_mfma_f32_16x16x32_bf16 v[158:161], v[38:41], v[182:185], v[158:161]
	v_mfma_f32_16x16x32_bf16 v[154:157], v[46:49], v[182:185], v[154:157]
	v_mfma_f32_16x16x32_bf16 v[142:145], v[38:41], v[224:227], v[142:145]
	v_mfma_f32_16x16x32_bf16 v[138:141], v[46:49], v[224:227], v[138:141]
	v_mfma_f32_16x16x32_bf16 v[126:129], v[38:41], v[242:245], v[126:129]
	v_mfma_f32_16x16x32_bf16 v[122:125], v[46:49], v[242:245], v[122:125]
	v_mfma_f32_16x16x32_bf16 v[110:113], v[38:41], v[250:253], v[110:113]
	v_mfma_f32_16x16x32_bf16 v[106:109], v[46:49], v[250:253], v[106:109]
	s_nop 0
	s_nop 0
	v_mfma_f32_16x16x32_bf16 v[150:153], v[50:53], v[172:175], v[150:153]
	v_mfma_f32_16x16x32_bf16 v[146:149], v[58:61], v[172:175], v[146:149]
	v_mfma_f32_16x16x32_bf16 v[134:137], v[50:53], v[220:223], v[134:137]
	v_mfma_f32_16x16x32_bf16 v[130:133], v[58:61], v[220:223], v[130:133]
	v_mfma_f32_16x16x32_bf16 v[118:121], v[50:53], v[228:231], v[118:121]
	v_mfma_f32_16x16x32_bf16 v[114:117], v[58:61], v[228:231], v[114:117]
	v_mfma_f32_16x16x32_bf16 v[102:105], v[50:53], v[246:249], v[102:105]
	v_mfma_f32_16x16x32_bf16 v[98:101], v[58:61], v[246:249], v[98:101]
	v_mfma_f32_16x16x32_bf16 v[150:153], v[54:57], v[182:185], v[150:153]
	v_mfma_f32_16x16x32_bf16 v[146:149], v[62:65], v[182:185], v[146:149]
	v_mfma_f32_16x16x32_bf16 v[134:137], v[54:57], v[224:227], v[134:137]
	v_mfma_f32_16x16x32_bf16 v[130:133], v[62:65], v[224:227], v[130:133]
	v_mfma_f32_16x16x32_bf16 v[118:121], v[54:57], v[242:245], v[118:121]
	v_mfma_f32_16x16x32_bf16 v[114:117], v[62:65], v[242:245], v[114:117]
	v_mfma_f32_16x16x32_bf16 v[102:105], v[54:57], v[250:253], v[102:105]
	v_mfma_f32_16x16x32_bf16 v[98:101], v[62:65], v[250:253], v[98:101]
	s_nop 0
	s_barrier
	s_add_i32 s60, s60, s50
	v_lshl_add_u64 v[176:177], s[2:3], 0, v[0:1]
	s_mov_b32 m0, s60
	ds_read_b128 v[172:175], v181 offset:16384
	ds_read_b128 v[182:185], v181 offset:17408
	ds_read_b128 v[220:223], v181 offset:18432
	ds_read_b128 v[224:227], v181 offset:19456
	ds_read_b128 v[228:231], v181 offset:20480
	ds_read_b128 v[242:245], v181 offset:21504
	ds_read_b128 v[246:249], v181 offset:22528
	ds_read_b128 v[250:253], v181 offset:23552
	global_load_lds_dwordx4 v[176:177], off
	s_add_i32 m0, s60, 0x2000
	s_add_u32 vcc_lo, s2, 0x40000
	v_lshl_add_u64 v[186:187], s[2:3], 0, v[162:163]
	s_addc_u32 vcc_hi, s3, 0
	s_add_i32 s60, s61, s50
	global_load_lds_dwordx4 v[186:187], off
	v_lshl_add_u64 v[196:197], vcc, 0, v[0:1]
	s_mov_b32 m0, s60
	v_lshl_add_u64 v[240:241], s[42:43], 0, v[164:165]
	global_load_lds_dwordx4 v[196:197], off
	v_lshl_add_u64 v[196:197], vcc, 0, v[162:163]
	s_add_i32 m0, s60, 0x2000
	s_nop 0
	global_load_lds_dwordx4 v[196:197], off
	v_lshl_add_u64 v[196:197], s[42:43], 0, v[166:167]
	s_mov_b32 m0, s35
	s_nop 0
	global_load_lds_dwordx4 v[196:197], off
	s_mov_b32 m0, s52
	s_nop 0
	global_load_lds_dwordx4 v[240:241], off
	s_waitcnt vmcnt(8)
	s_waitcnt lgkmcnt(0)
	s_barrier
; #define PG8_STAGE(bufoff, gbase, voff) do { _Pragma("unroll") for (int _i = 0; _i < 2; ++_i) \
;         __builtin_amdgcn_global_load_lds((const unsigned*)((const char*)(gbase) + (voff)[_i]), (PG8_LAS unsigned*)(lds + (bufoff) + ldsw + _i * 8192), 16, 0, 0); } while (0)
; #define PG8_LDA(dst, b, h) do { _Pragma("unroll") for (int m = 0; m < 4; ++m) _Pragma("unroll") for (int k = 0; k < 2; ++k) dst[m][k] = *(const PG8_LAS bf16x8*)(lds + PG8_SA(b, h) + aoff + m * 2048 + k * 1024); } while (0)
; #define PG8_LDB(dst, b, h) do { _Pragma("unroll") for (int n = 0; n < 2; ++n) _Pragma("unroll") for (int k = 0; k < 2; ++k) dst[n][k] = *(const PG8_LAS bf16x8*)(lds + PG8_SB(b, h) + boff + n * 2048 + k * 1024); } while (0)
; #define PG8_MMA(ai, bj, At, Bt) do { __builtin_amdgcn_s_setprio(1); _Pragma("unroll") for (int m = 0; m < 4; ++m) _Pragma("unroll") for (int n = 0; n < 2; ++n) _Pragma("unroll") for (int k = 0; k < 2; ++k) \
;         acc[ai][bj][m][n] = __builtin_amdgcn_mfma_f32_16x16x32_bf16(Bt[n][k], At[m][k], acc[ai][bj][m][n], 0, 0, 0); __builtin_amdgcn_s_setprio(0); } while (0)
; #define PG8_WAIT_V(n) asm volatile("s_waitcnt vmcnt(" #n ")" ::: "memory")
; #define PG8_WAIT_L(n) asm volatile("s_waitcnt lgkmcnt(" #n ")" ::: "memory")
; #define PG8_BAR __builtin_amdgcn_s_barrier()
; #define PG8_SCHED __builtin_amdgcn_sched_barrier(0)
; template <class Epi, class Sched, bool ALIGN_EPI = false, bool SP2 = false>
; __device__ __forceinline__ void gemm_phase(PG8_LAS unsigned char* lds, const Gemm g, const Sched& S, const Epi& E, int wv) {
;     ...
;             PG8_WAIT_V(8); PG8_WAIT_L(0); PG8_BAR; PG8_MMA(1, 0, At, B0); PG8_MMA(1, 1, At, B1); PG8_BAR; PG8_SCHED;
;             PG8_LDB(B0, 1, 0); PG8_LDB(B1, 1, 1); PG8_SCHED; PG8_LDA(At, 1, 0); PG8_STAGE(PG8_SA(0, 1), a2 + hstepA, voffA);
;             PG8_WAIT_V(8); PG8_WAIT_L(0); PG8_BAR; PG8_MMA(0, 0, At, B0); PG8_MMA(0, 1, At, B1); PG8_BAR; PG8_SCHED;
	s_nop 0
	s_waitcnt lgkmcnt(0)
	v_mfma_f32_16x16x32_bf16 v[94:97], v[34:37], v[172:175], v[94:97]
	v_mfma_f32_16x16x32_bf16 v[90:93], v[42:45], v[172:175], v[90:93]
	v_mfma_f32_16x16x32_bf16 v[78:81], v[34:37], v[220:223], v[78:81]
	v_mfma_f32_16x16x32_bf16 v[74:77], v[42:45], v[220:223], v[74:77]
	v_mfma_f32_16x16x32_bf16 v[30:33], v[34:37], v[228:231], v[30:33]
	v_mfma_f32_16x16x32_bf16 v[26:29], v[42:45], v[228:231], v[26:29]
	v_mfma_f32_16x16x32_bf16 v[14:17], v[34:37], v[246:249], v[14:17]
	v_mfma_f32_16x16x32_bf16 v[10:13], v[42:45], v[246:249], v[10:13]
	v_mfma_f32_16x16x32_bf16 v[94:97], v[38:41], v[182:185], v[94:97]
	v_mfma_f32_16x16x32_bf16 v[90:93], v[46:49], v[182:185], v[90:93]
	v_mfma_f32_16x16x32_bf16 v[78:81], v[38:41], v[224:227], v[78:81]
	v_mfma_f32_16x16x32_bf16 v[74:77], v[46:49], v[224:227], v[74:77]
	v_mfma_f32_16x16x32_bf16 v[30:33], v[38:41], v[242:245], v[30:33]
	v_mfma_f32_16x16x32_bf16 v[26:29], v[46:49], v[242:245], v[26:29]
	v_mfma_f32_16x16x32_bf16 v[14:17], v[38:41], v[250:253], v[14:17]
	v_mfma_f32_16x16x32_bf16 v[10:13], v[46:49], v[250:253], v[10:13]
	s_nop 0
	s_nop 0
	v_mfma_f32_16x16x32_bf16 v[22:25], v[50:53], v[228:231], v[22:25]
	v_mfma_f32_16x16x32_bf16 v[18:21], v[58:61], v[228:231], v[18:21]
	v_mfma_f32_16x16x32_bf16 v[6:9], v[50:53], v[246:249], v[6:9]
	v_mfma_f32_16x16x32_bf16 v[2:5], v[58:61], v[246:249], v[2:5]
	v_mfma_f32_16x16x32_bf16 v[34:37], v[50:53], v[172:175], v[86:89]
	v_mfma_f32_16x16x32_bf16 v[38:41], v[58:61], v[172:175], v[82:85]
	v_mfma_f32_16x16x32_bf16 v[42:45], v[50:53], v[220:223], v[70:73]
	v_mfma_f32_16x16x32_bf16 v[46:49], v[58:61], v[220:223], v[66:69]
	v_mfma_f32_16x16x32_bf16 v[22:25], v[54:57], v[242:245], v[22:25]
	v_mfma_f32_16x16x32_bf16 v[18:21], v[62:65], v[242:245], v[18:21]
	v_mfma_f32_16x16x32_bf16 v[6:9], v[54:57], v[250:253], v[6:9]
	v_mfma_f32_16x16x32_bf16 v[2:5], v[62:65], v[250:253], v[2:5]
	v_mfma_f32_16x16x32_bf16 v[34:37], v[54:57], v[182:185], v[34:37]
	v_mfma_f32_16x16x32_bf16 v[38:41], v[62:65], v[182:185], v[38:41]
	v_mfma_f32_16x16x32_bf16 v[42:45], v[54:57], v[224:227], v[42:45]
	v_mfma_f32_16x16x32_bf16 v[46:49], v[62:65], v[224:227], v[46:49]
	s_nop 0
	s_barrier
	s_add_i32 s60, 0, 0x18000
	s_add_i32 s61, 0, 0x1c000
	v_add_u32_e32 v62, s60, v180
	v_add_u32_e32 v66, s61, v180
	ds_read_b128 v[50:53], v62
	ds_read_b128 v[54:57], v62 offset:1024
	ds_read_b128 v[58:61], v62 offset:2048
	ds_read_b128 v[62:65], v62 offset:3072
	ds_read_b128 v[172:175], v66
	ds_read_b128 v[182:185], v66 offset:1024
	ds_read_b128 v[220:223], v66 offset:2048
	ds_read_b128 v[224:227], v66 offset:3072
	s_add_u32 s42, s42, 0x40000
	s_addc_u32 s43, s43, 0
	s_mov_b32 m0, s53
	v_lshl_add_u64 v[232:233], s[42:43], 0, v[166:167]
	ds_read_b128 v[66:69], v181 offset:32768
	ds_read_b128 v[70:73], v181 offset:33792
	ds_read_b128 v[82:85], v181 offset:34816
	ds_read_b128 v[86:89], v181 offset:35840
	ds_read_b128 v[228:231], v181 offset:36864
	ds_read_b128 v[242:245], v181 offset:37888
	ds_read_b128 v[246:249], v181 offset:38912
	ds_read_b128 v[250:253], v181 offset:39936
	global_load_lds_dwordx4 v[232:233], off
	v_lshl_add_u64 v[232:233], s[42:43], 0, v[164:165]
	s_mov_b32 m0, s55
	s_nop 0
	global_load_lds_dwordx4 v[232:233], off
	s_waitcnt vmcnt(8)
	s_waitcnt lgkmcnt(0)
	s_barrier
	s_nop 0
	s_waitcnt lgkmcnt(0)
	v_mfma_f32_16x16x32_bf16 v[158:161], v[50:53], v[66:69], v[158:161]
	v_mfma_f32_16x16x32_bf16 v[154:157], v[58:61], v[66:69], v[154:157]
	v_mfma_f32_16x16x32_bf16 v[142:145], v[50:53], v[82:85], v[142:145]
	v_mfma_f32_16x16x32_bf16 v[138:141], v[58:61], v[82:85], v[138:141]
	v_mfma_f32_16x16x32_bf16 v[126:129], v[50:53], v[228:231], v[126:129]
	v_mfma_f32_16x16x32_bf16 v[122:125], v[58:61], v[228:231], v[122:125]
	v_mfma_f32_16x16x32_bf16 v[110:113], v[50:53], v[246:249], v[110:113]
	v_mfma_f32_16x16x32_bf16 v[106:109], v[58:61], v[246:249], v[106:109]
	v_mfma_f32_16x16x32_bf16 v[158:161], v[54:57], v[70:73], v[158:161]
	v_mfma_f32_16x16x32_bf16 v[154:157], v[62:65], v[70:73], v[154:157]
	v_mfma_f32_16x16x32_bf16 v[142:145], v[54:57], v[86:89], v[142:145]
	v_mfma_f32_16x16x32_bf16 v[138:141], v[62:65], v[86:89], v[138:141]
	v_mfma_f32_16x16x32_bf16 v[126:129], v[54:57], v[242:245], v[126:129]
	v_mfma_f32_16x16x32_bf16 v[122:125], v[62:65], v[242:245], v[122:125]
	v_mfma_f32_16x16x32_bf16 v[110:113], v[54:57], v[250:253], v[110:113]
	v_mfma_f32_16x16x32_bf16 v[106:109], v[62:65], v[250:253], v[106:109]
	s_nop 0
	s_nop 0
	v_mfma_f32_16x16x32_bf16 v[150:153], v[172:175], v[66:69], v[150:153]
	v_mfma_f32_16x16x32_bf16 v[66:69], v[220:223], v[66:69], v[146:149]
	v_mfma_f32_16x16x32_bf16 v[146:149], v[224:227], v[70:73], v[66:69]
	v_mfma_f32_16x16x32_bf16 v[66:69], v[172:175], v[82:85], v[134:137]
	v_mfma_f32_16x16x32_bf16 v[134:137], v[182:185], v[86:89], v[66:69]
	v_mfma_f32_16x16x32_bf16 v[66:69], v[220:223], v[82:85], v[130:133]
	v_mfma_f32_16x16x32_bf16 v[130:133], v[224:227], v[86:89], v[66:69]
	v_mfma_f32_16x16x32_bf16 v[66:69], v[172:175], v[228:231], v[118:121]
	v_mfma_f32_16x16x32_bf16 v[118:121], v[182:185], v[242:245], v[66:69]
	v_mfma_f32_16x16x32_bf16 v[66:69], v[220:223], v[228:231], v[114:117]
	v_mfma_f32_16x16x32_bf16 v[114:117], v[224:227], v[242:245], v[66:69]
	v_mfma_f32_16x16x32_bf16 v[66:69], v[172:175], v[246:249], v[102:105]
	v_mfma_f32_16x16x32_bf16 v[102:105], v[182:185], v[250:253], v[66:69]
	v_mfma_f32_16x16x32_bf16 v[66:69], v[220:223], v[246:249], v[98:101]
	v_mfma_f32_16x16x32_bf16 v[150:153], v[182:185], v[70:73], v[150:153]
	v_mfma_f32_16x16x32_bf16 v[98:101], v[224:227], v[250:253], v[66:69]
	s_nop 0
	s_barrier
; #define PG8_STAGE(bufoff, gbase, voff) do { _Pragma("unroll") for (int _i = 0; _i < 2; ++_i) \
;         __builtin_amdgcn_global_load_lds((const unsigned*)((const char*)(gbase) + (voff)[_i]), (PG8_LAS unsigned*)(lds + (bufoff) + ldsw + _i * 8192), 16, 0, 0); } while (0)
; #define PG8_LDA(dst, b, h) do { _Pragma("unroll") for (int m = 0; m < 4; ++m) _Pragma("unroll") for (int k = 0; k < 2; ++k) dst[m][k] = *(const PG8_LAS bf16x8*)(lds + PG8_SA(b, h) + aoff + m * 2048 + k * 1024); } while (0)
; #define PG8_MMA(ai, bj, At, Bt) do { __builtin_amdgcn_s_setprio(1); _Pragma("unroll") for (int m = 0; m < 4; ++m) _Pragma("unroll") for (int n = 0; n < 2; ++n) _Pragma("unroll") for (int k = 0; k < 2; ++k) \
;         acc[ai][bj][m][n] = __builtin_amdgcn_mfma_f32_16x16x32_bf16(Bt[n][k], At[m][k], acc[ai][bj][m][n], 0, 0, 0); __builtin_amdgcn_s_setprio(0); } while (0)
; #define PG8_WAIT_V(n) asm volatile("s_waitcnt vmcnt(" #n ")" ::: "memory")
; #define PG8_WAIT_L(n) asm volatile("s_waitcnt lgkmcnt(" #n ")" ::: "memory")
; #define PG8_BAR __builtin_amdgcn_s_barrier()
; #define PG8_SCHED __builtin_amdgcn_sched_barrier(0)
; template <class Epi, class Sched, bool ALIGN_EPI = false, bool SP2 = false>
; __device__ __forceinline__ void gemm_phase(PG8_LAS unsigned char* lds, const Gemm g, const Sched& S, const Epi& E, int wv) {
;     ...
;         for (int t = 0; t < nt; t += 2) {
;             const bool last = (t == nt - 2);
;     ...
;             PG8_LDA(At, 1, 1); PG8_STAGE(PG8_SB(1, 0), b3, voffB); PG8_STAGE(PG8_SB(1, 1), b3 + hstepB, voffB); PG8_STAGE(PG8_SA(1, 0), a3, voffA);
;             PG8_WAIT_V(8); PG8_WAIT_L(0); PG8_BAR; PG8_MMA(1, 0, At, B0); PG8_MMA(1, 1, At, B1); PG8_BAR; PG8_SCHED;
	s_add_i32 s42, s60, s50
	v_lshl_add_u64 v[82:83], v[176:177], 0, s[62:63]
	s_mov_b32 m0, s42
	s_nop 0
	ds_read_b128 v[66:69], v181 offset:49152
	ds_read_b128 v[70:73], v181 offset:50176
	ds_read_b128 v[228:231], v181 offset:51200
	ds_read_b128 v[242:245], v181 offset:52224
	ds_read_b128 v[246:249], v181 offset:53248
	ds_read_b128 v[250:253], v181 offset:54272
	ds_read_b128 v[232:235], v181 offset:55296
	ds_read_b128 v[236:239], v181 offset:56320
	global_load_lds_dwordx4 v[82:83], off
	s_add_i32 m0, s42, 0x2000
	s_add_u32 s2, s2, 0x40080
	v_lshl_add_u64 v[82:83], v[186:187], 0, s[62:63]
	s_addc_u32 s3, s3, 0
	s_add_i32 s42, s61, s50
	global_load_lds_dwordx4 v[82:83], off
	v_lshl_add_u64 v[82:83], s[2:3], 0, v[0:1]
	s_mov_b32 m0, s42
	s_nop 0
	global_load_lds_dwordx4 v[82:83], off
	v_lshl_add_u64 v[82:83], s[2:3], 0, v[162:163]
	s_add_i32 m0, s42, 0x2000
	s_nop 0
	global_load_lds_dwordx4 v[82:83], off
	v_lshl_add_u64 v[82:83], v[196:197], 0, s[62:63]
	s_mov_b32 m0, s83
	s_nop 0
	global_load_lds_dwordx4 v[82:83], off
	v_lshl_add_u64 v[82:83], v[240:241], 0, s[62:63]
	s_mov_b32 m0, s87
	s_nop 0
	global_load_lds_dwordx4 v[82:83], off
	s_waitcnt vmcnt(8)
	s_waitcnt lgkmcnt(0)
	s_barrier
	s_nop 0
	s_waitcnt lgkmcnt(0)
	v_mfma_f32_16x16x32_bf16 v[82:85], v[50:53], v[66:69], v[94:97]
	v_mfma_f32_16x16x32_bf16 v[94:97], v[54:57], v[70:73], v[82:85]
	v_mfma_f32_16x16x32_bf16 v[82:85], v[58:61], v[66:69], v[90:93]
	v_mfma_f32_16x16x32_bf16 v[78:81], v[50:53], v[228:231], v[78:81]
	v_mfma_f32_16x16x32_bf16 v[74:77], v[58:61], v[228:231], v[74:77]
	v_mfma_f32_16x16x32_bf16 v[30:33], v[50:53], v[246:249], v[30:33]
	v_mfma_f32_16x16x32_bf16 v[26:29], v[58:61], v[246:249], v[26:29]
	v_mfma_f32_16x16x32_bf16 v[14:17], v[50:53], v[232:235], v[14:17]
	v_mfma_f32_16x16x32_bf16 v[10:13], v[58:61], v[232:235], v[10:13]
	v_mfma_f32_16x16x32_bf16 v[90:93], v[62:65], v[70:73], v[82:85]
	v_mfma_f32_16x16x32_bf16 v[78:81], v[54:57], v[242:245], v[78:81]
	v_mfma_f32_16x16x32_bf16 v[74:77], v[62:65], v[242:245], v[74:77]
	v_mfma_f32_16x16x32_bf16 v[30:33], v[54:57], v[250:253], v[30:33]
	v_mfma_f32_16x16x32_bf16 v[26:29], v[62:65], v[250:253], v[26:29]
	v_mfma_f32_16x16x32_bf16 v[14:17], v[54:57], v[236:239], v[14:17]
	v_mfma_f32_16x16x32_bf16 v[10:13], v[62:65], v[236:239], v[10:13]
	s_nop 0
	s_nop 0
	v_mfma_f32_16x16x32_bf16 v[34:37], v[172:175], v[66:69], v[34:37]
	v_mfma_f32_16x16x32_bf16 v[86:89], v[182:185], v[70:73], v[34:37]
	v_mfma_f32_16x16x32_bf16 v[34:37], v[220:223], v[66:69], v[38:41]
	v_mfma_f32_16x16x32_bf16 v[82:85], v[224:227], v[70:73], v[34:37]
	v_mfma_f32_16x16x32_bf16 v[34:37], v[172:175], v[228:231], v[42:45]
	v_mfma_f32_16x16x32_bf16 v[70:73], v[182:185], v[242:245], v[34:37]
	v_mfma_f32_16x16x32_bf16 v[34:37], v[220:223], v[228:231], v[46:49]
	v_mfma_f32_16x16x32_bf16 v[22:25], v[172:175], v[246:249], v[22:25]
	v_mfma_f32_16x16x32_bf16 v[18:21], v[220:223], v[246:249], v[18:21]
	v_mfma_f32_16x16x32_bf16 v[6:9], v[172:175], v[232:235], v[6:9]
	v_mfma_f32_16x16x32_bf16 v[2:5], v[220:223], v[232:235], v[2:5]
	v_mfma_f32_16x16x32_bf16 v[66:69], v[224:227], v[242:245], v[34:37]
	v_mfma_f32_16x16x32_bf16 v[22:25], v[182:185], v[250:253], v[22:25]
	v_mfma_f32_16x16x32_bf16 v[18:21], v[224:227], v[250:253], v[18:21]
	v_mfma_f32_16x16x32_bf16 v[6:9], v[182:185], v[236:239], v[6:9]
	v_mfma_f32_16x16x32_bf16 v[2:5], v[224:227], v[236:239], v[2:5]
	s_nop 0
	s_barrier
	s_add_i32 s96, s96, 2
	s_add_u32 s40, s40, 0x100
	s_addc_u32 s41, s41, 0
	s_add_u32 s94, s94, 0x100
	s_addc_u32 s95, s95, 0
	s_cmp_gt_u32 s96, 13
	s_cbranch_scc0 .LBB0_1893
	s_and_b64 vcc, exec, s[28:29]
	s_cbranch_vccz .LBB0_1896
	s_barrier

; #define PG8_STAGE(bufoff, gbase, voff) do { _Pragma("unroll") for (int _i = 0; _i < 2; ++_i) \
;         __builtin_amdgcn_global_load_lds((const unsigned*)((const char*)(gbase) + (voff)[_i]), (PG8_LAS unsigned*)(lds + (bufoff) + ldsw + _i * 8192), 16, 0, 0); } while (0)
; #define PG8_LDA(dst, b, h) do { _Pragma("unroll") for (int m = 0; m < 4; ++m) _Pragma("unroll") for (int k = 0; k < 2; ++k) dst[m][k] = *(const PG8_LAS bf16x8*)(lds + PG8_SA(b, h) + aoff + m * 2048 + k * 1024); } while (0)
; #define PG8_LDB(dst, b, h) do { _Pragma("unroll") for (int n = 0; n < 2; ++n) _Pragma("unroll") for (int k = 0; k < 2; ++k) dst[n][k] = *(const PG8_LAS bf16x8*)(lds + PG8_SB(b, h) + boff + n * 2048 + k * 1024); } while (0)
; #define PG8_MMA(ai, bj, At, Bt) do { __builtin_amdgcn_s_setprio(1); _Pragma("unroll") for (int m = 0; m < 4; ++m) _Pragma("unroll") for (int n = 0; n < 2; ++n) _Pragma("unroll") for (int k = 0; k < 2; ++k) \
;         acc[ai][bj][m][n] = __builtin_amdgcn_mfma_f32_16x16x32_bf16(Bt[n][k], At[m][k], acc[ai][bj][m][n], 0, 0, 0); __builtin_amdgcn_s_setprio(0); } while (0)
; #define PG8_WAIT_V(n) asm volatile("s_waitcnt vmcnt(" #n ")" ::: "memory")
; #define PG8_WAIT_L(n) asm volatile("s_waitcnt lgkmcnt(" #n ")" ::: "memory")
; #define PG8_BAR __builtin_amdgcn_s_barrier()
; #define PG8_SCHED __builtin_amdgcn_sched_barrier(0)
; template <class Epi, class Sched, bool ALIGN_EPI = false, bool SP2 = false>
; __device__ __forceinline__ void gemm_phase(PG8_LAS unsigned char* lds, const Gemm g, const Sched& S, const Epi& E, int wv) {
;     ...
;             const bool last = (t == nt - 2);
;             const char* a1 = cA + (size_t)(t + 1) * kstep;
;             const char* a2 = last ? nA : cA + (size_t)(t + 2) * kstep; const char* b2 = last ? nB : cB + (size_t)(t + 2) * kstep;
;             const char* a3 = a2 + kstep; const char* b3 = b2 + kstep;
;             if (last && has_next) S.a_ready(nxt);
;             if constexpr (SP2) {
;             PG8_LDB(B0, 0, 0); PG8_LDB(B1, 0, 1); PG8_SCHED; PG8_LDA(At, 0, 0); PG8_STAGE(PG8_SA(1, 1), a1 + hstepA, voffA);
;             PG8_WAIT_V(8); PG8_WAIT_L(0); PG8_BAR; PG8_MMA(0, 0, At, B0); PG8_MMA(0, 1, At, B1); PG8_BAR; PG8_SCHED;
;             PG8_LDA(At, 0, 1); PG8_STAGE(PG8_SB(0, 0), b2, voffB); PG8_STAGE(PG8_SB(0, 1), b2 + hstepB, voffB); PG8_STAGE(PG8_SA(0, 0), a2, voffA);
.LBB0_1976:
	s_add_u32 s2, s34, 0x100
	s_addc_u32 s3, s35, 0
	s_add_i32 s60, 0, 0x10000
	s_cmp_eq_u32 vcc_lo, 40
	s_cselect_b32 s41, s47, s3
	s_cselect_b32 s40, s46, s2
	s_cselect_b32 s19, s49, s97
	s_cselect_b32 s18, s48, s96
	s_add_i32 s61, 0, 0x14000
	v_add_u32_e32 v152, s60, v160
	v_add_u32_e32 v156, s61, v160
	ds_read_b128 v[140:143], v152
	ds_read_b128 v[144:147], v152 offset:1024
	ds_read_b128 v[148:151], v152 offset:2048
	ds_read_b128 v[152:155], v152 offset:3072
	ds_read_b128 v[162:165], v156
	ds_read_b128 v[166:169], v156 offset:1024
	ds_read_b128 v[170:173], v156 offset:2048
	ds_read_b128 v[174:177], v156 offset:3072
	v_lshl_add_u64 v[156:157], s[34:35], 0, v[136:137]
	s_add_i32 m0, s51, 0xc000
	ds_read_b128 v[178:181], v161
	ds_read_b128 v[182:185], v161 offset:1024
	ds_read_b128 v[220:223], v161 offset:2048
	ds_read_b128 v[224:227], v161 offset:3072
	ds_read_b128 v[228:231], v161 offset:4096
	ds_read_b128 v[242:245], v161 offset:5120
	ds_read_b128 v[246:249], v161 offset:6144
	ds_read_b128 v[250:253], v161 offset:7168
	global_load_lds_dwordx4 v[156:157], off
	v_lshl_add_u64 v[156:157], s[34:35], 0, v[138:139]
	s_add_i32 m0, s51, 0xe000
	s_nop 0
	global_load_lds_dwordx4 v[156:157], off
	s_waitcnt vmcnt(8)
	s_waitcnt lgkmcnt(0)
	s_barrier
	s_nop 0
	s_waitcnt lgkmcnt(0)
	v_mfma_f32_16x16x32_bf16 v[126:129], v[140:143], v[178:181], v[126:129]
	v_mfma_f32_16x16x32_bf16 v[122:125], v[148:151], v[178:181], v[122:125]
	v_mfma_f32_16x16x32_bf16 v[110:113], v[140:143], v[220:223], v[110:113]
	v_mfma_f32_16x16x32_bf16 v[106:109], v[148:151], v[220:223], v[106:109]
	v_mfma_f32_16x16x32_bf16 v[94:97], v[140:143], v[228:231], v[94:97]
	v_mfma_f32_16x16x32_bf16 v[90:93], v[148:151], v[228:231], v[90:93]
	v_mfma_f32_16x16x32_bf16 v[78:81], v[140:143], v[246:249], v[78:81]
	v_mfma_f32_16x16x32_bf16 v[74:77], v[148:151], v[246:249], v[74:77]
	v_mfma_f32_16x16x32_bf16 v[126:129], v[144:147], v[182:185], v[126:129]
	v_mfma_f32_16x16x32_bf16 v[122:125], v[152:155], v[182:185], v[122:125]
	v_mfma_f32_16x16x32_bf16 v[110:113], v[144:147], v[224:227], v[110:113]
	v_mfma_f32_16x16x32_bf16 v[106:109], v[152:155], v[224:227], v[106:109]
	v_mfma_f32_16x16x32_bf16 v[94:97], v[144:147], v[242:245], v[94:97]
	v_mfma_f32_16x16x32_bf16 v[90:93], v[152:155], v[242:245], v[90:93]
	v_mfma_f32_16x16x32_bf16 v[78:81], v[144:147], v[250:253], v[78:81]
	v_mfma_f32_16x16x32_bf16 v[74:77], v[152:155], v[250:253], v[74:77]
	s_nop 0
	s_nop 0
	v_mfma_f32_16x16x32_bf16 v[118:121], v[162:165], v[178:181], v[118:121]
	v_mfma_f32_16x16x32_bf16 v[114:117], v[170:173], v[178:181], v[114:117]
	v_mfma_f32_16x16x32_bf16 v[102:105], v[162:165], v[220:223], v[102:105]
	v_mfma_f32_16x16x32_bf16 v[98:101], v[170:173], v[220:223], v[98:101]
	v_mfma_f32_16x16x32_bf16 v[86:89], v[162:165], v[228:231], v[86:89]
	v_mfma_f32_16x16x32_bf16 v[82:85], v[170:173], v[228:231], v[82:85]
	v_mfma_f32_16x16x32_bf16 v[70:73], v[162:165], v[246:249], v[70:73]
	v_mfma_f32_16x16x32_bf16 v[66:69], v[170:173], v[246:249], v[66:69]
	v_mfma_f32_16x16x32_bf16 v[118:121], v[166:169], v[182:185], v[118:121]
	v_mfma_f32_16x16x32_bf16 v[114:117], v[174:177], v[182:185], v[114:117]
	v_mfma_f32_16x16x32_bf16 v[102:105], v[166:169], v[224:227], v[102:105]
	v_mfma_f32_16x16x32_bf16 v[98:101], v[174:177], v[224:227], v[98:101]
	v_mfma_f32_16x16x32_bf16 v[86:89], v[166:169], v[242:245], v[86:89]
	v_mfma_f32_16x16x32_bf16 v[82:85], v[174:177], v[242:245], v[82:85]
	v_mfma_f32_16x16x32_bf16 v[70:73], v[166:169], v[250:253], v[70:73]
	v_mfma_f32_16x16x32_bf16 v[66:69], v[174:177], v[250:253], v[66:69]
	s_nop 0
	s_barrier
	s_add_i32 s34, s60, s50
	v_lshl_add_u64 v[156:157], s[18:19], 0, v[0:1]
	s_mov_b32 m0, s34
	ds_read_b128 v[178:181], v161 offset:16384
	ds_read_b128 v[182:185], v161 offset:17408
	ds_read_b128 v[220:223], v161 offset:18432
	ds_read_b128 v[224:227], v161 offset:19456
	ds_read_b128 v[228:231], v161 offset:20480
	ds_read_b128 v[242:245], v161 offset:21504
	ds_read_b128 v[246:249], v161 offset:22528
	ds_read_b128 v[250:253], v161 offset:23552
	global_load_lds_dwordx4 v[156:157], off
	s_add_i32 m0, s34, 0x2000
	s_add_u32 s34, s18, 0xb0000
	v_lshl_add_u64 v[186:187], s[18:19], 0, v[134:135]
	s_addc_u32 s35, s19, 0
	s_add_i32 s60, s61, s50
	global_load_lds_dwordx4 v[186:187], off
	v_lshl_add_u64 v[196:197], s[34:35], 0, v[0:1]
	s_mov_b32 m0, s60
	v_lshl_add_u64 v[232:233], s[40:41], 0, v[132:133]
	global_load_lds_dwordx4 v[196:197], off
	v_lshl_add_u64 v[196:197], s[34:35], 0, v[134:135]
	s_add_i32 m0, s60, 0x2000
	s_nop 0
	global_load_lds_dwordx4 v[196:197], off
	v_lshl_add_u64 v[196:197], s[40:41], 0, v[130:131]
	s_mov_b32 m0, s51
	s_nop 0
	global_load_lds_dwordx4 v[196:197], off
	s_mov_b32 m0, s52
	s_nop 0
	global_load_lds_dwordx4 v[232:233], off
	s_waitcnt vmcnt(8)
	s_waitcnt lgkmcnt(0)
	s_barrier
; #define PG8_STAGE(bufoff, gbase, voff) do { _Pragma("unroll") for (int _i = 0; _i < 2; ++_i) \
;         __builtin_amdgcn_global_load_lds((const unsigned*)((const char*)(gbase) + (voff)[_i]), (PG8_LAS unsigned*)(lds + (bufoff) + ldsw + _i * 8192), 16, 0, 0); } while (0)
; #define PG8_LDA(dst, b, h) do { _Pragma("unroll") for (int m = 0; m < 4; ++m) _Pragma("unroll") for (int k = 0; k < 2; ++k) dst[m][k] = *(const PG8_LAS bf16x8*)(lds + PG8_SA(b, h) + aoff + m * 2048 + k * 1024); } while (0)
; #define PG8_LDB(dst, b, h) do { _Pragma("unroll") for (int n = 0; n < 2; ++n) _Pragma("unroll") for (int k = 0; k < 2; ++k) dst[n][k] = *(const PG8_LAS bf16x8*)(lds + PG8_SB(b, h) + boff + n * 2048 + k * 1024); } while (0)
; #define PG8_MMA(ai, bj, At, Bt) do { __builtin_amdgcn_s_setprio(1); _Pragma("unroll") for (int m = 0; m < 4; ++m) _Pragma("unroll") for (int n = 0; n < 2; ++n) _Pragma("unroll") for (int k = 0; k < 2; ++k) \
;         acc[ai][bj][m][n] = __builtin_amdgcn_mfma_f32_16x16x32_bf16(Bt[n][k], At[m][k], acc[ai][bj][m][n], 0, 0, 0); __builtin_amdgcn_s_setprio(0); } while (0)
; #define PG8_WAIT_V(n) asm volatile("s_waitcnt vmcnt(" #n ")" ::: "memory")
; #define PG8_WAIT_L(n) asm volatile("s_waitcnt lgkmcnt(" #n ")" ::: "memory")
; #define PG8_BAR __builtin_amdgcn_s_barrier()
; #define PG8_SCHED __builtin_amdgcn_sched_barrier(0)
; template <class Epi, class Sched, bool ALIGN_EPI = false, bool SP2 = false>
; __device__ __forceinline__ void gemm_phase(PG8_LAS unsigned char* lds, const Gemm g, const Sched& S, const Epi& E, int wv) {
;     ...
;             PG8_WAIT_V(8); PG8_WAIT_L(0); PG8_BAR; PG8_MMA(1, 0, At, B0); PG8_MMA(1, 1, At, B1); PG8_BAR; PG8_SCHED;
;             PG8_LDB(B0, 1, 0); PG8_LDB(B1, 1, 1); PG8_SCHED; PG8_LDA(At, 1, 0); PG8_STAGE(PG8_SA(0, 1), a2 + hstepA, voffA);
;             PG8_WAIT_V(8); PG8_WAIT_L(0); PG8_BAR; PG8_MMA(0, 0, At, B0); PG8_MMA(0, 1, At, B1); PG8_BAR; PG8_SCHED;
	s_nop 0
	s_waitcnt lgkmcnt(0)
	v_mfma_f32_16x16x32_bf16 v[62:65], v[140:143], v[178:181], v[62:65]
	v_mfma_f32_16x16x32_bf16 v[58:61], v[148:151], v[178:181], v[58:61]
	v_mfma_f32_16x16x32_bf16 v[46:49], v[140:143], v[220:223], v[46:49]
	v_mfma_f32_16x16x32_bf16 v[42:45], v[148:151], v[220:223], v[42:45]
	v_mfma_f32_16x16x32_bf16 v[30:33], v[140:143], v[228:231], v[30:33]
	v_mfma_f32_16x16x32_bf16 v[26:29], v[148:151], v[228:231], v[26:29]
	v_mfma_f32_16x16x32_bf16 v[14:17], v[140:143], v[246:249], v[14:17]
	v_mfma_f32_16x16x32_bf16 v[10:13], v[148:151], v[246:249], v[10:13]
	v_mfma_f32_16x16x32_bf16 v[62:65], v[144:147], v[182:185], v[62:65]
	v_mfma_f32_16x16x32_bf16 v[58:61], v[152:155], v[182:185], v[58:61]
	v_mfma_f32_16x16x32_bf16 v[46:49], v[144:147], v[224:227], v[46:49]
	v_mfma_f32_16x16x32_bf16 v[42:45], v[152:155], v[224:227], v[42:45]
	v_mfma_f32_16x16x32_bf16 v[30:33], v[144:147], v[242:245], v[30:33]
	v_mfma_f32_16x16x32_bf16 v[26:29], v[152:155], v[242:245], v[26:29]
	v_mfma_f32_16x16x32_bf16 v[14:17], v[144:147], v[250:253], v[14:17]
	v_mfma_f32_16x16x32_bf16 v[10:13], v[152:155], v[250:253], v[10:13]
	s_nop 0
	s_nop 0
	v_mfma_f32_16x16x32_bf16 v[54:57], v[162:165], v[178:181], v[54:57]
	v_mfma_f32_16x16x32_bf16 v[50:53], v[170:173], v[178:181], v[50:53]
	v_mfma_f32_16x16x32_bf16 v[38:41], v[162:165], v[220:223], v[38:41]
	v_mfma_f32_16x16x32_bf16 v[34:37], v[170:173], v[220:223], v[34:37]
	v_mfma_f32_16x16x32_bf16 v[22:25], v[162:165], v[228:231], v[22:25]
	v_mfma_f32_16x16x32_bf16 v[18:21], v[170:173], v[228:231], v[18:21]
	v_mfma_f32_16x16x32_bf16 v[6:9], v[162:165], v[246:249], v[6:9]
	v_mfma_f32_16x16x32_bf16 v[2:5], v[170:173], v[246:249], v[2:5]
	v_mfma_f32_16x16x32_bf16 v[54:57], v[166:169], v[182:185], v[54:57]
	v_mfma_f32_16x16x32_bf16 v[50:53], v[174:177], v[182:185], v[50:53]
	v_mfma_f32_16x16x32_bf16 v[38:41], v[166:169], v[224:227], v[38:41]
	v_mfma_f32_16x16x32_bf16 v[34:37], v[174:177], v[224:227], v[34:37]
	v_mfma_f32_16x16x32_bf16 v[22:25], v[166:169], v[242:245], v[22:25]
	v_mfma_f32_16x16x32_bf16 v[18:21], v[174:177], v[242:245], v[18:21]
	v_mfma_f32_16x16x32_bf16 v[6:9], v[166:169], v[250:253], v[6:9]
	v_mfma_f32_16x16x32_bf16 v[2:5], v[174:177], v[250:253], v[2:5]
	s_nop 0
	s_barrier
	s_add_i32 s60, 0, 0x18000
	s_add_i32 s61, 0, 0x1c000
	v_add_u32_e32 v152, s60, v160
	v_add_u32_e32 v174, s61, v160
	ds_read_b128 v[140:143], v152
	ds_read_b128 v[144:147], v152 offset:1024
	ds_read_b128 v[148:151], v152 offset:2048
	ds_read_b128 v[152:155], v152 offset:3072
	ds_read_b128 v[162:165], v174
	ds_read_b128 v[166:169], v174 offset:1024
	ds_read_b128 v[170:173], v174 offset:2048
	ds_read_b128 v[174:177], v174 offset:3072
	s_add_u32 s34, s40, 0xb0000
	s_addc_u32 s35, s41, 0
	s_mov_b32 m0, s53
	v_lshl_add_u64 v[234:235], s[34:35], 0, v[130:131]
	ds_read_b128 v[178:181], v161 offset:32768
	ds_read_b128 v[182:185], v161 offset:33792
	ds_read_b128 v[220:223], v161 offset:34816
	ds_read_b128 v[224:227], v161 offset:35840
	ds_read_b128 v[228:231], v161 offset:36864
	ds_read_b128 v[242:245], v161 offset:37888
	ds_read_b128 v[246:249], v161 offset:38912
	ds_read_b128 v[250:253], v161 offset:39936
	global_load_lds_dwordx4 v[234:235], off
	v_lshl_add_u64 v[234:235], s[34:35], 0, v[132:133]
	s_mov_b32 m0, s55
	s_nop 0
	global_load_lds_dwordx4 v[234:235], off
	s_waitcnt vmcnt(8)
	s_waitcnt lgkmcnt(0)
	s_barrier
	s_nop 0
	s_waitcnt lgkmcnt(0)
	v_mfma_f32_16x16x32_bf16 v[126:129], v[140:143], v[178:181], v[126:129]
	v_mfma_f32_16x16x32_bf16 v[122:125], v[148:151], v[178:181], v[122:125]
	v_mfma_f32_16x16x32_bf16 v[110:113], v[140:143], v[220:223], v[110:113]
	v_mfma_f32_16x16x32_bf16 v[106:109], v[148:151], v[220:223], v[106:109]
	v_mfma_f32_16x16x32_bf16 v[94:97], v[140:143], v[228:231], v[94:97]
	v_mfma_f32_16x16x32_bf16 v[90:93], v[148:151], v[228:231], v[90:93]
	v_mfma_f32_16x16x32_bf16 v[78:81], v[140:143], v[246:249], v[78:81]
	v_mfma_f32_16x16x32_bf16 v[74:77], v[148:151], v[246:249], v[74:77]
	v_mfma_f32_16x16x32_bf16 v[126:129], v[144:147], v[182:185], v[126:129]
	v_mfma_f32_16x16x32_bf16 v[122:125], v[152:155], v[182:185], v[122:125]
	v_mfma_f32_16x16x32_bf16 v[110:113], v[144:147], v[224:227], v[110:113]
	v_mfma_f32_16x16x32_bf16 v[106:109], v[152:155], v[224:227], v[106:109]
	v_mfma_f32_16x16x32_bf16 v[94:97], v[144:147], v[242:245], v[94:97]
	v_mfma_f32_16x16x32_bf16 v[90:93], v[152:155], v[242:245], v[90:93]
	v_mfma_f32_16x16x32_bf16 v[78:81], v[144:147], v[250:253], v[78:81]
	v_mfma_f32_16x16x32_bf16 v[74:77], v[152:155], v[250:253], v[74:77]
	s_nop 0
	s_nop 0
	v_mfma_f32_16x16x32_bf16 v[118:121], v[162:165], v[178:181], v[118:121]
	v_mfma_f32_16x16x32_bf16 v[114:117], v[170:173], v[178:181], v[114:117]
	v_mfma_f32_16x16x32_bf16 v[102:105], v[162:165], v[220:223], v[102:105]
	v_mfma_f32_16x16x32_bf16 v[98:101], v[170:173], v[220:223], v[98:101]
	v_mfma_f32_16x16x32_bf16 v[86:89], v[162:165], v[228:231], v[86:89]
	v_mfma_f32_16x16x32_bf16 v[82:85], v[170:173], v[228:231], v[82:85]
	v_mfma_f32_16x16x32_bf16 v[70:73], v[162:165], v[246:249], v[70:73]
	v_mfma_f32_16x16x32_bf16 v[66:69], v[170:173], v[246:249], v[66:69]
	v_mfma_f32_16x16x32_bf16 v[118:121], v[166:169], v[182:185], v[118:121]
	v_mfma_f32_16x16x32_bf16 v[114:117], v[174:177], v[182:185], v[114:117]
	v_mfma_f32_16x16x32_bf16 v[102:105], v[166:169], v[224:227], v[102:105]
	v_mfma_f32_16x16x32_bf16 v[98:101], v[174:177], v[224:227], v[98:101]
	v_mfma_f32_16x16x32_bf16 v[86:89], v[166:169], v[242:245], v[86:89]
	v_mfma_f32_16x16x32_bf16 v[82:85], v[174:177], v[242:245], v[82:85]
	v_mfma_f32_16x16x32_bf16 v[70:73], v[166:169], v[250:253], v[70:73]
	v_mfma_f32_16x16x32_bf16 v[66:69], v[174:177], v[250:253], v[66:69]
	s_nop 0
	s_barrier
; #define PG8_STAGE(bufoff, gbase, voff) do { _Pragma("unroll") for (int _i = 0; _i < 2; ++_i) \
;         __builtin_amdgcn_global_load_lds((const unsigned*)((const char*)(gbase) + (voff)[_i]), (PG8_LAS unsigned*)(lds + (bufoff) + ldsw + _i * 8192), 16, 0, 0); } while (0)
; #define PG8_LDA(dst, b, h) do { _Pragma("unroll") for (int m = 0; m < 4; ++m) _Pragma("unroll") for (int k = 0; k < 2; ++k) dst[m][k] = *(const PG8_LAS bf16x8*)(lds + PG8_SA(b, h) + aoff + m * 2048 + k * 1024); } while (0)
; #define PG8_MMA(ai, bj, At, Bt) do { __builtin_amdgcn_s_setprio(1); _Pragma("unroll") for (int m = 0; m < 4; ++m) _Pragma("unroll") for (int n = 0; n < 2; ++n) _Pragma("unroll") for (int k = 0; k < 2; ++k) \
;         acc[ai][bj][m][n] = __builtin_amdgcn_mfma_f32_16x16x32_bf16(Bt[n][k], At[m][k], acc[ai][bj][m][n], 0, 0, 0); __builtin_amdgcn_s_setprio(0); } while (0)
; #define PG8_WAIT_V(n) asm volatile("s_waitcnt vmcnt(" #n ")" ::: "memory")
; #define PG8_WAIT_L(n) asm volatile("s_waitcnt lgkmcnt(" #n ")" ::: "memory")
; #define PG8_BAR __builtin_amdgcn_s_barrier()
; #define PG8_SCHED __builtin_amdgcn_sched_barrier(0)
; template <class Epi, class Sched, bool ALIGN_EPI = false, bool SP2 = false>
; __device__ __forceinline__ void gemm_phase(PG8_LAS unsigned char* lds, const Gemm g, const Sched& S, const Epi& E, int wv) {
;     ...
;         for (int t = 0; t < nt; t += 2) {
;             const bool last = (t == nt - 2);
;     ...
;             PG8_LDA(At, 1, 1); PG8_STAGE(PG8_SB(1, 0), b3, voffB); PG8_STAGE(PG8_SB(1, 1), b3 + hstepB, voffB); PG8_STAGE(PG8_SA(1, 0), a3, voffA);
;             PG8_WAIT_V(8); PG8_WAIT_L(0); PG8_BAR; PG8_MMA(1, 0, At, B0); PG8_MMA(1, 1, At, B1); PG8_BAR; PG8_SCHED;
	s_add_i32 s34, s60, s50
	v_lshl_add_u64 v[156:157], v[156:157], 0, s[62:63]
	s_mov_b32 m0, s34
	ds_read_b128 v[178:181], v161 offset:49152
	ds_read_b128 v[182:185], v161 offset:50176
	ds_read_b128 v[220:223], v161 offset:51200
	ds_read_b128 v[224:227], v161 offset:52224
	ds_read_b128 v[228:231], v161 offset:53248
	ds_read_b128 v[242:245], v161 offset:54272
	ds_read_b128 v[246:249], v161 offset:55296
	ds_read_b128 v[250:253], v161 offset:56320
	global_load_lds_dwordx4 v[156:157], off
	s_add_i32 m0, s34, 0x2000
	s_add_u32 s18, s18, 0xb0080
	v_lshl_add_u64 v[156:157], v[186:187], 0, s[62:63]
	s_addc_u32 s19, s19, 0
	s_add_i32 s34, s61, s50
	global_load_lds_dwordx4 v[156:157], off
	v_lshl_add_u64 v[156:157], s[18:19], 0, v[0:1]
	s_mov_b32 m0, s34
	s_nop 0
	global_load_lds_dwordx4 v[156:157], off
	v_lshl_add_u64 v[156:157], s[18:19], 0, v[134:135]
	s_add_i32 m0, s34, 0x2000
	s_nop 0
	global_load_lds_dwordx4 v[156:157], off
	v_lshl_add_u64 v[156:157], v[196:197], 0, s[62:63]
	s_mov_b32 m0, s83
	s_nop 0
	global_load_lds_dwordx4 v[156:157], off
	v_lshl_add_u64 v[156:157], v[232:233], 0, s[62:63]
	s_mov_b32 m0, s87
	s_nop 0
	global_load_lds_dwordx4 v[156:157], off
	s_waitcnt vmcnt(8)
	s_waitcnt lgkmcnt(0)
	s_barrier
	s_nop 0
	s_waitcnt lgkmcnt(0)
	v_mfma_f32_16x16x32_bf16 v[62:65], v[140:143], v[178:181], v[62:65]
	v_mfma_f32_16x16x32_bf16 v[58:61], v[148:151], v[178:181], v[58:61]
	v_mfma_f32_16x16x32_bf16 v[46:49], v[140:143], v[220:223], v[46:49]
	v_mfma_f32_16x16x32_bf16 v[42:45], v[148:151], v[220:223], v[42:45]
	v_mfma_f32_16x16x32_bf16 v[30:33], v[140:143], v[228:231], v[30:33]
	v_mfma_f32_16x16x32_bf16 v[26:29], v[148:151], v[228:231], v[26:29]
	v_mfma_f32_16x16x32_bf16 v[14:17], v[140:143], v[246:249], v[14:17]
	v_mfma_f32_16x16x32_bf16 v[10:13], v[148:151], v[246:249], v[10:13]
	v_mfma_f32_16x16x32_bf16 v[62:65], v[144:147], v[182:185], v[62:65]
	v_mfma_f32_16x16x32_bf16 v[58:61], v[152:155], v[182:185], v[58:61]
	v_mfma_f32_16x16x32_bf16 v[46:49], v[144:147], v[224:227], v[46:49]
	v_mfma_f32_16x16x32_bf16 v[42:45], v[152:155], v[224:227], v[42:45]
	v_mfma_f32_16x16x32_bf16 v[30:33], v[144:147], v[242:245], v[30:33]
	v_mfma_f32_16x16x32_bf16 v[26:29], v[152:155], v[242:245], v[26:29]
	v_mfma_f32_16x16x32_bf16 v[14:17], v[144:147], v[250:253], v[14:17]
	v_mfma_f32_16x16x32_bf16 v[10:13], v[152:155], v[250:253], v[10:13]
	s_nop 0
	s_nop 0
	v_mfma_f32_16x16x32_bf16 v[54:57], v[162:165], v[178:181], v[54:57]
	v_mfma_f32_16x16x32_bf16 v[50:53], v[170:173], v[178:181], v[50:53]
	v_mfma_f32_16x16x32_bf16 v[38:41], v[162:165], v[220:223], v[38:41]
	v_mfma_f32_16x16x32_bf16 v[34:37], v[170:173], v[220:223], v[34:37]
	v_mfma_f32_16x16x32_bf16 v[22:25], v[162:165], v[228:231], v[22:25]
	v_mfma_f32_16x16x32_bf16 v[18:21], v[170:173], v[228:231], v[18:21]
	v_mfma_f32_16x16x32_bf16 v[6:9], v[162:165], v[246:249], v[6:9]
	v_mfma_f32_16x16x32_bf16 v[2:5], v[170:173], v[246:249], v[2:5]
	v_mfma_f32_16x16x32_bf16 v[54:57], v[166:169], v[182:185], v[54:57]
	v_mfma_f32_16x16x32_bf16 v[50:53], v[174:177], v[182:185], v[50:53]
	v_mfma_f32_16x16x32_bf16 v[38:41], v[166:169], v[224:227], v[38:41]
	v_mfma_f32_16x16x32_bf16 v[34:37], v[174:177], v[224:227], v[34:37]
	v_mfma_f32_16x16x32_bf16 v[22:25], v[166:169], v[242:245], v[22:25]
	v_mfma_f32_16x16x32_bf16 v[18:21], v[174:177], v[242:245], v[18:21]
	v_mfma_f32_16x16x32_bf16 v[6:9], v[166:169], v[250:253], v[6:9]
	v_mfma_f32_16x16x32_bf16 v[2:5], v[174:177], v[250:253], v[2:5]
	s_nop 0
	s_barrier
	s_add_i32 vcc_lo, vcc_lo, 2
	s_add_u32 s96, s96, 0x100
	s_addc_u32 s97, s97, 0
	s_cmp_gt_u32 vcc_lo, 41
	s_mov_b64 s[34:35], s[2:3]
	s_cbranch_scc0 .LBB0_1976
	s_and_b64 vcc, exec, s[38:39]
	s_cbranch_vccz .LBB0_1979
	s_barrier
